# v31 + all GEMM K-loops: s_setprio 1 issued before the pre-compute barrier (wave parks already prioritized) and the redundant post-barrier lgkmcnt(0) removed, so the first MFMA issues right at barrier
# speedup vs baseline: 1.0081x; 1.0081x over previous
.LBB0_246:
	s_add_u32 s3, s34, 0xfff80080
	s_addc_u32 s6, s35, -1
	s_add_i32 s7, 0, 0x10000
	s_cmp_eq_u32 s2, 28
	s_cselect_b32 s43, s15, s6
	s_cselect_b32 s42, s47, s3
	s_cselect_b32 s39, s13, s50
	s_cselect_b32 s38, s48, s49
	s_add_i32 s3, 0, 0x14000
	v_add_u32_e32 v156, s7, v145
	v_add_u32_e32 v172, s3, v145
	ds_read_b128 v[140:143], v156
	ds_read_b128 v[148:151], v156 offset:1024
	ds_read_b128 v[152:155], v156 offset:2048
	ds_read_b128 v[156:159], v156 offset:3072
	ds_read_b128 v[160:163], v172
	ds_read_b128 v[164:167], v172 offset:1024
	ds_read_b128 v[168:171], v172 offset:2048
	ds_read_b128 v[172:175], v172 offset:3072
	v_lshl_add_u64 v[176:177], s[34:35], 0, v[136:137]
	s_add_i32 m0, s18, 0xc000
	ds_read_b128 v[182:185], v147
	ds_read_b128 v[186:189], v147 offset:1024
	ds_read_b128 v[190:193], v147 offset:2048
	ds_read_b128 v[214:217], v147 offset:3072
	ds_read_b128 v[218:221], v147 offset:4096
	ds_read_b128 v[222:225], v147 offset:5120
	ds_read_b128 v[226:229], v147 offset:6144
	ds_read_b128 v[230:233], v147 offset:7168
	global_load_lds_dwordx4 v[176:177], off
	v_lshl_add_u64 v[176:177], s[34:35], 0, v[138:139]
	s_add_i32 m0, s18, 0xe000
	s_nop 0
	global_load_lds_dwordx4 v[176:177], off
	s_setprio 1
	s_waitcnt vmcnt(8)
	s_waitcnt lgkmcnt(0)
	s_barrier
	v_mfma_f32_16x16x32_bf16 v[126:129], v[140:143], v[182:185], v[126:129]
	v_mfma_f32_16x16x32_bf16 v[122:125], v[152:155], v[182:185], v[122:125]
	v_mfma_f32_16x16x32_bf16 v[118:121], v[140:143], v[190:193], v[118:121]
	v_mfma_f32_16x16x32_bf16 v[110:113], v[152:155], v[190:193], v[110:113]
	v_mfma_f32_16x16x32_bf16 v[102:105], v[140:143], v[218:221], v[102:105]
	v_mfma_f32_16x16x32_bf16 v[92:95], v[152:155], v[218:221], v[92:95]
	v_mfma_f32_16x16x32_bf16 v[84:87], v[140:143], v[226:229], v[84:87]
	v_mfma_f32_16x16x32_bf16 v[76:79], v[152:155], v[226:229], v[76:79]
	v_mfma_f32_16x16x32_bf16 v[126:129], v[148:151], v[186:189], v[126:129]
	v_mfma_f32_16x16x32_bf16 v[122:125], v[156:159], v[186:189], v[122:125]
	v_mfma_f32_16x16x32_bf16 v[118:121], v[148:151], v[214:217], v[118:121]
	v_mfma_f32_16x16x32_bf16 v[110:113], v[156:159], v[214:217], v[110:113]
	v_mfma_f32_16x16x32_bf16 v[102:105], v[148:151], v[222:225], v[102:105]
	v_mfma_f32_16x16x32_bf16 v[92:95], v[156:159], v[222:225], v[92:95]
	v_mfma_f32_16x16x32_bf16 v[84:87], v[148:151], v[230:233], v[84:87]
	v_mfma_f32_16x16x32_bf16 v[76:79], v[156:159], v[230:233], v[76:79]
	s_setprio 0
	s_setprio 1
	v_mfma_f32_16x16x32_bf16 v[114:117], v[160:163], v[182:185], v[114:117]
	v_mfma_f32_16x16x32_bf16 v[106:109], v[168:171], v[182:185], v[106:109]
	v_mfma_f32_16x16x32_bf16 v[98:101], v[160:163], v[190:193], v[98:101]
	v_mfma_f32_16x16x32_bf16 v[88:91], v[168:171], v[190:193], v[88:91]
	v_mfma_f32_16x16x32_bf16 v[80:83], v[160:163], v[218:221], v[80:83]
	v_mfma_f32_16x16x32_bf16 v[72:75], v[168:171], v[218:221], v[72:75]
	v_mfma_f32_16x16x32_bf16 v[68:71], v[160:163], v[226:229], v[68:71]
	v_mfma_f32_16x16x32_bf16 v[64:67], v[168:171], v[226:229], v[64:67]
	v_mfma_f32_16x16x32_bf16 v[114:117], v[164:167], v[186:189], v[114:117]
	v_mfma_f32_16x16x32_bf16 v[106:109], v[172:175], v[186:189], v[106:109]
	v_mfma_f32_16x16x32_bf16 v[98:101], v[164:167], v[214:217], v[98:101]
	v_mfma_f32_16x16x32_bf16 v[88:91], v[172:175], v[214:217], v[88:91]
	v_mfma_f32_16x16x32_bf16 v[80:83], v[164:167], v[222:225], v[80:83]
	v_mfma_f32_16x16x32_bf16 v[72:75], v[172:175], v[222:225], v[72:75]
	v_mfma_f32_16x16x32_bf16 v[68:71], v[164:167], v[230:233], v[68:71]
	v_mfma_f32_16x16x32_bf16 v[64:67], v[172:175], v[230:233], v[64:67]
	s_setprio 0
	s_barrier
	s_add_i32 s6, s7, s17
	v_lshl_add_u64 v[176:177], s[38:39], 0, v[96:97]
	s_mov_b32 m0, s6
	ds_read_b128 v[182:185], v147 offset:16384
	ds_read_b128 v[186:189], v147 offset:17408
	ds_read_b128 v[190:193], v147 offset:18432
	ds_read_b128 v[214:217], v147 offset:19456
	ds_read_b128 v[218:221], v147 offset:20480
	ds_read_b128 v[222:225], v147 offset:21504
	ds_read_b128 v[226:229], v147 offset:22528
	ds_read_b128 v[230:233], v147 offset:23552
	global_load_lds_dwordx4 v[176:177], off
	s_add_i32 m0, s6, 0x2000
	s_add_u32 s6, s38, 0x80000
	v_lshl_add_u64 v[178:179], s[38:39], 0, v[130:131]
	s_addc_u32 s7, s39, 0
	s_add_i32 s3, s3, s17
	global_load_lds_dwordx4 v[178:179], off
	v_lshl_add_u64 v[180:181], s[6:7], 0, v[96:97]
	s_mov_b32 m0, s3
	v_lshl_add_u64 v[194:195], s[42:43], 0, v[132:133]
	global_load_lds_dwordx4 v[180:181], off
	v_lshl_add_u64 v[180:181], s[6:7], 0, v[130:131]
	s_add_i32 m0, s3, 0x2000
	s_nop 0
	global_load_lds_dwordx4 v[180:181], off
	v_lshl_add_u64 v[180:181], s[42:43], 0, v[134:135]
	s_mov_b32 m0, s18
	s_nop 0
	global_load_lds_dwordx4 v[180:181], off
	s_mov_b32 m0, s19
	s_nop 0
	global_load_lds_dwordx4 v[194:195], off
	s_setprio 1
	s_waitcnt vmcnt(8)
	s_waitcnt lgkmcnt(0)
	s_barrier
	v_mfma_f32_16x16x32_bf16 v[60:63], v[140:143], v[182:185], v[60:63]
	v_mfma_f32_16x16x32_bf16 v[56:59], v[152:155], v[182:185], v[56:59]
	v_mfma_f32_16x16x32_bf16 v[52:55], v[140:143], v[190:193], v[52:55]
	v_mfma_f32_16x16x32_bf16 v[44:47], v[152:155], v[190:193], v[44:47]
	v_mfma_f32_16x16x32_bf16 v[36:39], v[140:143], v[218:221], v[36:39]
	v_mfma_f32_16x16x32_bf16 v[28:31], v[152:155], v[218:221], v[28:31]
	v_mfma_f32_16x16x32_bf16 v[20:23], v[140:143], v[226:229], v[20:23]
	v_mfma_f32_16x16x32_bf16 v[12:15], v[152:155], v[226:229], v[12:15]
	v_mfma_f32_16x16x32_bf16 v[60:63], v[148:151], v[186:189], v[60:63]
	v_mfma_f32_16x16x32_bf16 v[56:59], v[156:159], v[186:189], v[56:59]
	v_mfma_f32_16x16x32_bf16 v[52:55], v[148:151], v[214:217], v[52:55]
	v_mfma_f32_16x16x32_bf16 v[44:47], v[156:159], v[214:217], v[44:47]
	v_mfma_f32_16x16x32_bf16 v[36:39], v[148:151], v[222:225], v[36:39]
	v_mfma_f32_16x16x32_bf16 v[28:31], v[156:159], v[222:225], v[28:31]
	v_mfma_f32_16x16x32_bf16 v[20:23], v[148:151], v[230:233], v[20:23]
	v_mfma_f32_16x16x32_bf16 v[12:15], v[156:159], v[230:233], v[12:15]
	s_setprio 0
	s_setprio 1
	v_mfma_f32_16x16x32_bf16 v[48:51], v[160:163], v[182:185], v[48:51]
	v_mfma_f32_16x16x32_bf16 v[40:43], v[168:171], v[182:185], v[40:43]
	v_mfma_f32_16x16x32_bf16 v[32:35], v[160:163], v[190:193], v[32:35]
	v_mfma_f32_16x16x32_bf16 v[24:27], v[168:171], v[190:193], v[24:27]
	v_mfma_f32_16x16x32_bf16 v[16:19], v[160:163], v[218:221], v[16:19]
	v_mfma_f32_16x16x32_bf16 v[8:11], v[168:171], v[218:221], v[8:11]
	v_mfma_f32_16x16x32_bf16 v[4:7], v[160:163], v[226:229], v[4:7]
	v_mfma_f32_16x16x32_bf16 v[0:3], v[168:171], v[226:229], v[0:3]
	v_mfma_f32_16x16x32_bf16 v[48:51], v[164:167], v[186:189], v[48:51]
	v_mfma_f32_16x16x32_bf16 v[40:43], v[172:175], v[186:189], v[40:43]
	v_mfma_f32_16x16x32_bf16 v[32:35], v[164:167], v[214:217], v[32:35]
	v_mfma_f32_16x16x32_bf16 v[24:27], v[172:175], v[214:217], v[24:27]
	v_mfma_f32_16x16x32_bf16 v[16:19], v[164:167], v[222:225], v[16:19]
	v_mfma_f32_16x16x32_bf16 v[8:11], v[172:175], v[222:225], v[8:11]
	v_mfma_f32_16x16x32_bf16 v[4:7], v[164:167], v[230:233], v[4:7]
	v_mfma_f32_16x16x32_bf16 v[0:3], v[172:175], v[230:233], v[0:3]
	s_setprio 0
	s_barrier
	s_add_i32 s3, 0, 0x18000
	s_add_i32 s51, 0, 0x1c000
	v_add_u32_e32 v156, s3, v145
	v_add_u32_e32 v172, s51, v145
	ds_read_b128 v[140:143], v156
	ds_read_b128 v[148:151], v156 offset:1024
	ds_read_b128 v[152:155], v156 offset:2048
	ds_read_b128 v[156:159], v156 offset:3072
	ds_read_b128 v[160:163], v172
	ds_read_b128 v[164:167], v172 offset:1024
	ds_read_b128 v[168:171], v172 offset:2048
	ds_read_b128 v[172:175], v172 offset:3072
	s_add_u32 s6, s42, 0x80000
	s_addc_u32 s7, s43, 0
	s_mov_b32 m0, s20
	v_lshl_add_u64 v[202:203], s[6:7], 0, v[134:135]
	ds_read_b128 v[182:185], v147 offset:32768
	ds_read_b128 v[186:189], v147 offset:33792
	ds_read_b128 v[190:193], v147 offset:34816
	ds_read_b128 v[214:217], v147 offset:35840
	ds_read_b128 v[218:221], v147 offset:36864
	ds_read_b128 v[222:225], v147 offset:37888
	ds_read_b128 v[226:229], v147 offset:38912
	ds_read_b128 v[230:233], v147 offset:39936
	global_load_lds_dwordx4 v[202:203], off
	v_lshl_add_u64 v[202:203], s[6:7], 0, v[132:133]
	s_mov_b32 m0, s36
	s_nop 0
	global_load_lds_dwordx4 v[202:203], off
	s_setprio 1
	s_waitcnt vmcnt(8)
	s_waitcnt lgkmcnt(0)
	s_barrier
	v_mfma_f32_16x16x32_bf16 v[126:129], v[140:143], v[182:185], v[126:129]
	v_mfma_f32_16x16x32_bf16 v[122:125], v[152:155], v[182:185], v[122:125]
	v_mfma_f32_16x16x32_bf16 v[118:121], v[140:143], v[190:193], v[118:121]
	v_mfma_f32_16x16x32_bf16 v[110:113], v[152:155], v[190:193], v[110:113]
	v_mfma_f32_16x16x32_bf16 v[102:105], v[140:143], v[218:221], v[102:105]
	v_mfma_f32_16x16x32_bf16 v[92:95], v[152:155], v[218:221], v[92:95]
	v_mfma_f32_16x16x32_bf16 v[84:87], v[140:143], v[226:229], v[84:87]
	v_mfma_f32_16x16x32_bf16 v[76:79], v[152:155], v[226:229], v[76:79]
	v_mfma_f32_16x16x32_bf16 v[126:129], v[148:151], v[186:189], v[126:129]
	v_mfma_f32_16x16x32_bf16 v[122:125], v[156:159], v[186:189], v[122:125]
	v_mfma_f32_16x16x32_bf16 v[118:121], v[148:151], v[214:217], v[118:121]
	v_mfma_f32_16x16x32_bf16 v[110:113], v[156:159], v[214:217], v[110:113]
	v_mfma_f32_16x16x32_bf16 v[102:105], v[148:151], v[222:225], v[102:105]
	v_mfma_f32_16x16x32_bf16 v[92:95], v[156:159], v[222:225], v[92:95]
	v_mfma_f32_16x16x32_bf16 v[84:87], v[148:151], v[230:233], v[84:87]
	v_mfma_f32_16x16x32_bf16 v[76:79], v[156:159], v[230:233], v[76:79]
	s_setprio 0
	s_setprio 1
	v_mfma_f32_16x16x32_bf16 v[114:117], v[160:163], v[182:185], v[114:117]
	v_mfma_f32_16x16x32_bf16 v[106:109], v[168:171], v[182:185], v[106:109]
	v_mfma_f32_16x16x32_bf16 v[98:101], v[160:163], v[190:193], v[98:101]
	v_mfma_f32_16x16x32_bf16 v[88:91], v[168:171], v[190:193], v[88:91]
	v_mfma_f32_16x16x32_bf16 v[80:83], v[160:163], v[218:221], v[80:83]
	v_mfma_f32_16x16x32_bf16 v[72:75], v[168:171], v[218:221], v[72:75]
	v_mfma_f32_16x16x32_bf16 v[68:71], v[160:163], v[226:229], v[68:71]
	v_mfma_f32_16x16x32_bf16 v[64:67], v[168:171], v[226:229], v[64:67]
	v_mfma_f32_16x16x32_bf16 v[114:117], v[164:167], v[186:189], v[114:117]
	v_mfma_f32_16x16x32_bf16 v[106:109], v[172:175], v[186:189], v[106:109]
	v_mfma_f32_16x16x32_bf16 v[98:101], v[164:167], v[214:217], v[98:101]
	v_mfma_f32_16x16x32_bf16 v[88:91], v[172:175], v[214:217], v[88:91]
	v_mfma_f32_16x16x32_bf16 v[80:83], v[164:167], v[222:225], v[80:83]
	v_mfma_f32_16x16x32_bf16 v[72:75], v[172:175], v[222:225], v[72:75]
	v_mfma_f32_16x16x32_bf16 v[68:71], v[164:167], v[230:233], v[68:71]
	v_mfma_f32_16x16x32_bf16 v[64:67], v[172:175], v[230:233], v[64:67]
	s_setprio 0
	s_barrier
	s_add_i32 s3, s3, s17
	v_lshl_add_u64 v[176:177], v[176:177], 0, s[30:31]
	s_mov_b32 m0, s3
	ds_read_b128 v[182:185], v147 offset:49152
	ds_read_b128 v[186:189], v147 offset:50176
	ds_read_b128 v[190:193], v147 offset:51200
	ds_read_b128 v[214:217], v147 offset:52224
	ds_read_b128 v[218:221], v147 offset:53248
	ds_read_b128 v[222:225], v147 offset:54272
	ds_read_b128 v[226:229], v147 offset:55296
	ds_read_b128 v[230:233], v147 offset:56320
	global_load_lds_dwordx4 v[176:177], off
	s_add_i32 m0, s3, 0x2000
	s_add_u32 s6, s38, 0x80080
	v_lshl_add_u64 v[176:177], v[178:179], 0, s[30:31]
	s_addc_u32 s7, s39, 0
	s_add_i32 s3, s51, s17
	global_load_lds_dwordx4 v[176:177], off
	v_lshl_add_u64 v[176:177], s[6:7], 0, v[96:97]
	s_mov_b32 m0, s3
	s_nop 0
	global_load_lds_dwordx4 v[176:177], off
	v_lshl_add_u64 v[176:177], s[6:7], 0, v[130:131]
	s_add_i32 m0, s3, 0x2000
	s_nop 0
	global_load_lds_dwordx4 v[176:177], off
	v_lshl_add_u64 v[176:177], v[180:181], 0, s[30:31]
	s_mov_b32 m0, s37
	s_nop 0
	global_load_lds_dwordx4 v[176:177], off
	v_lshl_add_u64 v[176:177], v[194:195], 0, s[30:31]
	s_mov_b32 m0, s40
	s_nop 0
	global_load_lds_dwordx4 v[176:177], off
	s_setprio 1
	s_waitcnt vmcnt(8)
	s_waitcnt lgkmcnt(0)
	s_barrier
	v_mfma_f32_16x16x32_bf16 v[60:63], v[140:143], v[182:185], v[60:63]
	v_mfma_f32_16x16x32_bf16 v[56:59], v[152:155], v[182:185], v[56:59]
	v_mfma_f32_16x16x32_bf16 v[52:55], v[140:143], v[190:193], v[52:55]
	v_mfma_f32_16x16x32_bf16 v[44:47], v[152:155], v[190:193], v[44:47]
	v_mfma_f32_16x16x32_bf16 v[36:39], v[140:143], v[218:221], v[36:39]
	v_mfma_f32_16x16x32_bf16 v[28:31], v[152:155], v[218:221], v[28:31]
	v_mfma_f32_16x16x32_bf16 v[20:23], v[140:143], v[226:229], v[20:23]
	v_mfma_f32_16x16x32_bf16 v[12:15], v[152:155], v[226:229], v[12:15]
	v_mfma_f32_16x16x32_bf16 v[60:63], v[148:151], v[186:189], v[60:63]
	v_mfma_f32_16x16x32_bf16 v[56:59], v[156:159], v[186:189], v[56:59]
	v_mfma_f32_16x16x32_bf16 v[52:55], v[148:151], v[214:217], v[52:55]
	v_mfma_f32_16x16x32_bf16 v[44:47], v[156:159], v[214:217], v[44:47]
	v_mfma_f32_16x16x32_bf16 v[36:39], v[148:151], v[222:225], v[36:39]
	v_mfma_f32_16x16x32_bf16 v[28:31], v[156:159], v[222:225], v[28:31]
	v_mfma_f32_16x16x32_bf16 v[20:23], v[148:151], v[230:233], v[20:23]
	v_mfma_f32_16x16x32_bf16 v[12:15], v[156:159], v[230:233], v[12:15]
	s_setprio 0
	s_setprio 1
	v_mfma_f32_16x16x32_bf16 v[48:51], v[160:163], v[182:185], v[48:51]
	v_mfma_f32_16x16x32_bf16 v[40:43], v[168:171], v[182:185], v[40:43]
	v_mfma_f32_16x16x32_bf16 v[32:35], v[160:163], v[190:193], v[32:35]
	v_mfma_f32_16x16x32_bf16 v[24:27], v[168:171], v[190:193], v[24:27]
	v_mfma_f32_16x16x32_bf16 v[16:19], v[160:163], v[218:221], v[16:19]
	v_mfma_f32_16x16x32_bf16 v[8:11], v[168:171], v[218:221], v[8:11]
	v_mfma_f32_16x16x32_bf16 v[4:7], v[160:163], v[226:229], v[4:7]
	v_mfma_f32_16x16x32_bf16 v[0:3], v[168:171], v[226:229], v[0:3]
	v_mfma_f32_16x16x32_bf16 v[48:51], v[164:167], v[186:189], v[48:51]
	v_mfma_f32_16x16x32_bf16 v[40:43], v[172:175], v[186:189], v[40:43]
	v_mfma_f32_16x16x32_bf16 v[32:35], v[164:167], v[214:217], v[32:35]
	v_mfma_f32_16x16x32_bf16 v[24:27], v[172:175], v[214:217], v[24:27]
	v_mfma_f32_16x16x32_bf16 v[16:19], v[164:167], v[222:225], v[16:19]
	v_mfma_f32_16x16x32_bf16 v[8:11], v[172:175], v[222:225], v[8:11]
	v_mfma_f32_16x16x32_bf16 v[4:7], v[164:167], v[230:233], v[4:7]
	v_mfma_f32_16x16x32_bf16 v[0:3], v[172:175], v[230:233], v[0:3]
	s_setprio 0
	s_barrier
	s_add_i32 s2, s2, 2
	s_add_u32 s34, s34, 0x100
	s_addc_u32 s35, s35, 0
	s_add_u32 s49, s49, 0x100
	s_addc_u32 s50, s50, 0
	s_cmp_gt_u32 s2, 29
	s_cbranch_scc0 .LBB0_246
	s_nop 0
	s_nop 0
	s_nop 0
	s_nop 0
	s_and_b64 vcc, exec, s[10:11]
	s_cbranch_vccz .LBB0_249
	s_barrier

.LBB0_421:
	s_add_u32 s3, s22, 0xfffe0080
	s_addc_u32 s6, s23, -1
	s_add_i32 s7, 0, 0x10000
	s_cmp_eq_u32 s2, 4
	s_cselect_b32 s35, s4, s6
	s_cselect_b32 s34, s5, s3
	v_add_u32_e32 v96, s7, v176
	s_cselect_b32 s25, s9, s17
	s_cselect_b32 s24, s13, s15
	s_add_i32 s3, 0, 0x14000
	ds_read_b128 v[56:59], v96
	ds_read_b128 v[60:63], v96 offset:1024
	ds_read_b128 v[138:141], v96 offset:2048
	ds_read_b128 v[142:145], v96 offset:3072
	v_add_u32_e32 v96, s3, v176
	ds_read_b128 v[146:149], v96
	ds_read_b128 v[150:153], v96 offset:1024
	ds_read_b128 v[154:157], v96 offset:2048
	ds_read_b128 v[170:173], v96 offset:3072
	v_lshl_add_u64 v[174:175], s[22:23], 0, v[166:167]
	s_add_i32 m0, s75, 0xc000
	ds_read_b128 v[182:185], v177
	ds_read_b128 v[186:189], v177 offset:1024
	ds_read_b128 v[190:193], v177 offset:2048
	ds_read_b128 v[214:217], v177 offset:3072
	ds_read_b128 v[218:221], v177 offset:4096
	ds_read_b128 v[222:225], v177 offset:5120
	ds_read_b128 v[226:229], v177 offset:6144
	ds_read_b128 v[230:233], v177 offset:7168
	global_load_lds_dwordx4 v[174:175], off
	v_lshl_add_u64 v[174:175], s[22:23], 0, v[168:169]
	s_add_i32 m0, s75, 0xe000
	s_nop 0
	global_load_lds_dwordx4 v[174:175], off
	s_setprio 1
	s_waitcnt vmcnt(8)
	s_waitcnt lgkmcnt(0)
	s_barrier
	v_mfma_f32_16x16x32_bf16 v[134:137], v[56:59], v[182:185], v[134:137]
	v_mfma_f32_16x16x32_bf16 v[130:133], v[138:141], v[182:185], v[130:133]
	v_mfma_f32_16x16x32_bf16 v[118:121], v[56:59], v[190:193], v[118:121]
	v_mfma_f32_16x16x32_bf16 v[114:117], v[138:141], v[190:193], v[114:117]
	v_mfma_f32_16x16x32_bf16 v[102:105], v[56:59], v[218:221], v[102:105]
	v_mfma_f32_16x16x32_bf16 v[98:101], v[138:141], v[218:221], v[98:101]
	v_mfma_f32_16x16x32_bf16 v[84:87], v[56:59], v[226:229], v[84:87]
	v_mfma_f32_16x16x32_bf16 v[80:83], v[138:141], v[226:229], v[80:83]
	v_mfma_f32_16x16x32_bf16 v[134:137], v[60:63], v[186:189], v[134:137]
	v_mfma_f32_16x16x32_bf16 v[130:133], v[142:145], v[186:189], v[130:133]
	v_mfma_f32_16x16x32_bf16 v[118:121], v[60:63], v[214:217], v[118:121]
	v_mfma_f32_16x16x32_bf16 v[114:117], v[142:145], v[214:217], v[114:117]
	v_mfma_f32_16x16x32_bf16 v[102:105], v[60:63], v[222:225], v[102:105]
	v_mfma_f32_16x16x32_bf16 v[98:101], v[142:145], v[222:225], v[98:101]
	v_mfma_f32_16x16x32_bf16 v[84:87], v[60:63], v[230:233], v[84:87]
	v_mfma_f32_16x16x32_bf16 v[80:83], v[142:145], v[230:233], v[80:83]
	s_setprio 0
	s_setprio 1
	v_mfma_f32_16x16x32_bf16 v[126:129], v[146:149], v[182:185], v[126:129]
	v_mfma_f32_16x16x32_bf16 v[122:125], v[154:157], v[182:185], v[122:125]
	v_mfma_f32_16x16x32_bf16 v[110:113], v[146:149], v[190:193], v[110:113]
	v_mfma_f32_16x16x32_bf16 v[106:109], v[154:157], v[190:193], v[106:109]
	v_mfma_f32_16x16x32_bf16 v[92:95], v[146:149], v[218:221], v[92:95]
	v_mfma_f32_16x16x32_bf16 v[88:91], v[154:157], v[218:221], v[88:91]
	v_mfma_f32_16x16x32_bf16 v[76:79], v[146:149], v[226:229], v[76:79]
	v_mfma_f32_16x16x32_bf16 v[72:75], v[154:157], v[226:229], v[72:75]
	v_mfma_f32_16x16x32_bf16 v[126:129], v[150:153], v[186:189], v[126:129]
	v_mfma_f32_16x16x32_bf16 v[122:125], v[170:173], v[186:189], v[122:125]
	v_mfma_f32_16x16x32_bf16 v[110:113], v[150:153], v[214:217], v[110:113]
	v_mfma_f32_16x16x32_bf16 v[106:109], v[170:173], v[214:217], v[106:109]
	v_mfma_f32_16x16x32_bf16 v[92:95], v[150:153], v[222:225], v[92:95]
	v_mfma_f32_16x16x32_bf16 v[88:91], v[170:173], v[222:225], v[88:91]
	v_mfma_f32_16x16x32_bf16 v[76:79], v[150:153], v[230:233], v[76:79]
	v_mfma_f32_16x16x32_bf16 v[72:75], v[170:173], v[230:233], v[72:75]
	s_setprio 0
	s_barrier
	s_add_i32 s6, s7, s74
	v_lshl_add_u64 v[174:175], s[24:25], 0, v[160:161]
	s_mov_b32 m0, s6
	ds_read_b128 v[182:185], v177 offset:16384
	ds_read_b128 v[186:189], v177 offset:17408
	ds_read_b128 v[190:193], v177 offset:18432
	ds_read_b128 v[214:217], v177 offset:19456
	ds_read_b128 v[218:221], v177 offset:20480
	ds_read_b128 v[222:225], v177 offset:21504
	ds_read_b128 v[226:229], v177 offset:22528
	ds_read_b128 v[230:233], v177 offset:23552
	global_load_lds_dwordx4 v[174:175], off
	s_add_i32 m0, s6, 0x2000
	s_add_u32 s6, s24, 0x20000
	v_lshl_add_u64 v[178:179], s[24:25], 0, v[164:165]
	s_addc_u32 s7, s25, 0
	s_add_i32 s3, s3, s74
	global_load_lds_dwordx4 v[178:179], off
	v_lshl_add_u64 v[180:181], s[6:7], 0, v[160:161]
	s_mov_b32 m0, s3
	v_lshl_add_u64 v[194:195], s[34:35], 0, v[162:163]
	global_load_lds_dwordx4 v[180:181], off
	v_lshl_add_u64 v[180:181], s[6:7], 0, v[164:165]
	s_add_i32 m0, s3, 0x2000
	s_nop 0
	global_load_lds_dwordx4 v[180:181], off
	v_lshl_add_u64 v[180:181], s[34:35], 0, v[158:159]
	s_mov_b32 m0, s75
	s_nop 0
	global_load_lds_dwordx4 v[180:181], off
	s_mov_b32 m0, s82
	s_nop 0
	global_load_lds_dwordx4 v[194:195], off
	s_setprio 1
	s_waitcnt vmcnt(8)
	s_waitcnt lgkmcnt(0)
	s_barrier
	v_mfma_f32_16x16x32_bf16 v[68:71], v[56:59], v[182:185], v[68:71]
	v_mfma_f32_16x16x32_bf16 v[64:67], v[138:141], v[182:185], v[64:67]
	v_mfma_f32_16x16x32_bf16 v[44:47], v[56:59], v[190:193], v[44:47]
	v_mfma_f32_16x16x32_bf16 v[40:43], v[138:141], v[190:193], v[40:43]
	v_mfma_f32_16x16x32_bf16 v[28:31], v[56:59], v[218:221], v[28:31]
	v_mfma_f32_16x16x32_bf16 v[24:27], v[138:141], v[218:221], v[24:27]
	v_mfma_f32_16x16x32_bf16 v[12:15], v[56:59], v[226:229], v[12:15]
	v_mfma_f32_16x16x32_bf16 v[8:11], v[138:141], v[226:229], v[8:11]
	v_mfma_f32_16x16x32_bf16 v[68:71], v[60:63], v[186:189], v[68:71]
	v_mfma_f32_16x16x32_bf16 v[64:67], v[142:145], v[186:189], v[64:67]
	v_mfma_f32_16x16x32_bf16 v[44:47], v[60:63], v[214:217], v[44:47]
	v_mfma_f32_16x16x32_bf16 v[40:43], v[142:145], v[214:217], v[40:43]
	v_mfma_f32_16x16x32_bf16 v[28:31], v[60:63], v[222:225], v[28:31]
	v_mfma_f32_16x16x32_bf16 v[24:27], v[142:145], v[222:225], v[24:27]
	v_mfma_f32_16x16x32_bf16 v[12:15], v[60:63], v[230:233], v[12:15]
	v_mfma_f32_16x16x32_bf16 v[8:11], v[142:145], v[230:233], v[8:11]
	s_setprio 0
	s_setprio 1
	v_mfma_f32_16x16x32_bf16 v[52:55], v[146:149], v[182:185], v[52:55]
	v_mfma_f32_16x16x32_bf16 v[48:51], v[154:157], v[182:185], v[48:51]
	v_mfma_f32_16x16x32_bf16 v[36:39], v[146:149], v[190:193], v[36:39]
	v_mfma_f32_16x16x32_bf16 v[32:35], v[154:157], v[190:193], v[32:35]
	v_mfma_f32_16x16x32_bf16 v[20:23], v[146:149], v[218:221], v[20:23]
	v_mfma_f32_16x16x32_bf16 v[16:19], v[154:157], v[218:221], v[16:19]
	v_mfma_f32_16x16x32_bf16 v[4:7], v[146:149], v[226:229], v[4:7]
	v_mfma_f32_16x16x32_bf16 v[0:3], v[154:157], v[226:229], v[0:3]
	v_mfma_f32_16x16x32_bf16 v[52:55], v[150:153], v[186:189], v[52:55]
	v_mfma_f32_16x16x32_bf16 v[48:51], v[170:173], v[186:189], v[48:51]
	v_mfma_f32_16x16x32_bf16 v[36:39], v[150:153], v[214:217], v[36:39]
	v_mfma_f32_16x16x32_bf16 v[32:35], v[170:173], v[214:217], v[32:35]
	v_mfma_f32_16x16x32_bf16 v[20:23], v[150:153], v[222:225], v[20:23]
	v_mfma_f32_16x16x32_bf16 v[16:19], v[170:173], v[222:225], v[16:19]
	v_mfma_f32_16x16x32_bf16 v[4:7], v[150:153], v[230:233], v[4:7]
	v_mfma_f32_16x16x32_bf16 v[0:3], v[170:173], v[230:233], v[0:3]
	s_setprio 0
	s_barrier
	s_add_i32 s3, 0, 0x18000
	v_add_u32_e32 v96, s3, v176
	s_add_i32 s18, 0, 0x1c000
	ds_read_b128 v[56:59], v96
	ds_read_b128 v[60:63], v96 offset:1024
	ds_read_b128 v[138:141], v96 offset:2048
	ds_read_b128 v[142:145], v96 offset:3072
	v_add_u32_e32 v96, s18, v176
	ds_read_b128 v[146:149], v96
	ds_read_b128 v[150:153], v96 offset:1024
	ds_read_b128 v[154:157], v96 offset:2048
	ds_read_b128 v[170:173], v96 offset:3072
	s_add_u32 s6, s34, 0x20000
	s_addc_u32 s7, s35, 0
	s_mov_b32 m0, s83
	v_lshl_add_u64 v[202:203], s[6:7], 0, v[158:159]
	ds_read_b128 v[182:185], v177 offset:32768
	ds_read_b128 v[186:189], v177 offset:33792
	ds_read_b128 v[190:193], v177 offset:34816
	ds_read_b128 v[214:217], v177 offset:35840
	ds_read_b128 v[218:221], v177 offset:36864
	ds_read_b128 v[222:225], v177 offset:37888
	ds_read_b128 v[226:229], v177 offset:38912
	ds_read_b128 v[230:233], v177 offset:39936
	global_load_lds_dwordx4 v[202:203], off
	v_lshl_add_u64 v[202:203], s[6:7], 0, v[162:163]
	s_mov_b32 m0, s88
	s_nop 0
	global_load_lds_dwordx4 v[202:203], off
	s_setprio 1
	s_waitcnt vmcnt(8)
	s_waitcnt lgkmcnt(0)
	s_barrier
	v_mfma_f32_16x16x32_bf16 v[134:137], v[56:59], v[182:185], v[134:137]
	v_mfma_f32_16x16x32_bf16 v[130:133], v[138:141], v[182:185], v[130:133]
	v_mfma_f32_16x16x32_bf16 v[118:121], v[56:59], v[190:193], v[118:121]
	v_mfma_f32_16x16x32_bf16 v[114:117], v[138:141], v[190:193], v[114:117]
	v_mfma_f32_16x16x32_bf16 v[102:105], v[56:59], v[218:221], v[102:105]
	v_mfma_f32_16x16x32_bf16 v[98:101], v[138:141], v[218:221], v[98:101]
	v_mfma_f32_16x16x32_bf16 v[84:87], v[56:59], v[226:229], v[84:87]
	v_mfma_f32_16x16x32_bf16 v[80:83], v[138:141], v[226:229], v[80:83]
	v_mfma_f32_16x16x32_bf16 v[134:137], v[60:63], v[186:189], v[134:137]
	v_mfma_f32_16x16x32_bf16 v[130:133], v[142:145], v[186:189], v[130:133]
	v_mfma_f32_16x16x32_bf16 v[118:121], v[60:63], v[214:217], v[118:121]
	v_mfma_f32_16x16x32_bf16 v[114:117], v[142:145], v[214:217], v[114:117]
	v_mfma_f32_16x16x32_bf16 v[102:105], v[60:63], v[222:225], v[102:105]
	v_mfma_f32_16x16x32_bf16 v[98:101], v[142:145], v[222:225], v[98:101]
	v_mfma_f32_16x16x32_bf16 v[84:87], v[60:63], v[230:233], v[84:87]
	v_mfma_f32_16x16x32_bf16 v[80:83], v[142:145], v[230:233], v[80:83]
	s_setprio 0
	s_setprio 1
	v_mfma_f32_16x16x32_bf16 v[126:129], v[146:149], v[182:185], v[126:129]
	v_mfma_f32_16x16x32_bf16 v[122:125], v[154:157], v[182:185], v[122:125]
	v_mfma_f32_16x16x32_bf16 v[110:113], v[146:149], v[190:193], v[110:113]
	v_mfma_f32_16x16x32_bf16 v[106:109], v[154:157], v[190:193], v[106:109]
	v_mfma_f32_16x16x32_bf16 v[92:95], v[146:149], v[218:221], v[92:95]
	v_mfma_f32_16x16x32_bf16 v[88:91], v[154:157], v[218:221], v[88:91]
	v_mfma_f32_16x16x32_bf16 v[76:79], v[146:149], v[226:229], v[76:79]
	v_mfma_f32_16x16x32_bf16 v[72:75], v[154:157], v[226:229], v[72:75]
	v_mfma_f32_16x16x32_bf16 v[126:129], v[150:153], v[186:189], v[126:129]
	v_mfma_f32_16x16x32_bf16 v[122:125], v[170:173], v[186:189], v[122:125]
	v_mfma_f32_16x16x32_bf16 v[110:113], v[150:153], v[214:217], v[110:113]
	v_mfma_f32_16x16x32_bf16 v[106:109], v[170:173], v[214:217], v[106:109]
	v_mfma_f32_16x16x32_bf16 v[92:95], v[150:153], v[222:225], v[92:95]
	v_mfma_f32_16x16x32_bf16 v[88:91], v[170:173], v[222:225], v[88:91]
	v_mfma_f32_16x16x32_bf16 v[76:79], v[150:153], v[230:233], v[76:79]
	v_mfma_f32_16x16x32_bf16 v[72:75], v[170:173], v[230:233], v[72:75]
	s_setprio 0
	s_barrier
	s_add_i32 s3, s3, s74
	v_lshl_add_u64 v[174:175], v[174:175], 0, s[30:31]
	s_mov_b32 m0, s3
	ds_read_b128 v[182:185], v177 offset:49152
	ds_read_b128 v[186:189], v177 offset:50176
	ds_read_b128 v[190:193], v177 offset:51200
	ds_read_b128 v[214:217], v177 offset:52224
	ds_read_b128 v[218:221], v177 offset:53248
	ds_read_b128 v[222:225], v177 offset:54272
	ds_read_b128 v[226:229], v177 offset:55296
	ds_read_b128 v[230:233], v177 offset:56320
	global_load_lds_dwordx4 v[174:175], off
	s_add_i32 m0, s3, 0x2000
	s_add_u32 s6, s24, 0x20080
	v_lshl_add_u64 v[174:175], v[178:179], 0, s[30:31]
	s_addc_u32 s7, s25, 0
	s_add_i32 s3, s18, s74
	global_load_lds_dwordx4 v[174:175], off
	v_lshl_add_u64 v[174:175], s[6:7], 0, v[160:161]
	s_mov_b32 m0, s3
	s_nop 0
	global_load_lds_dwordx4 v[174:175], off
	v_lshl_add_u64 v[174:175], s[6:7], 0, v[164:165]
	s_add_i32 m0, s3, 0x2000
	s_nop 0
	global_load_lds_dwordx4 v[174:175], off
	v_lshl_add_u64 v[174:175], v[180:181], 0, s[30:31]
	s_mov_b32 m0, s97
	s_nop 0
	global_load_lds_dwordx4 v[174:175], off
	v_lshl_add_u64 v[174:175], v[194:195], 0, s[30:31]
	s_mov_b32 m0, s50
	s_nop 0
	global_load_lds_dwordx4 v[174:175], off
	s_setprio 1
	s_waitcnt vmcnt(8)
	s_waitcnt lgkmcnt(0)
	s_barrier
	v_mfma_f32_16x16x32_bf16 v[68:71], v[56:59], v[182:185], v[68:71]
	v_mfma_f32_16x16x32_bf16 v[64:67], v[138:141], v[182:185], v[64:67]
	v_mfma_f32_16x16x32_bf16 v[44:47], v[56:59], v[190:193], v[44:47]
	v_mfma_f32_16x16x32_bf16 v[40:43], v[138:141], v[190:193], v[40:43]
	v_mfma_f32_16x16x32_bf16 v[28:31], v[56:59], v[218:221], v[28:31]
	v_mfma_f32_16x16x32_bf16 v[24:27], v[138:141], v[218:221], v[24:27]
	v_mfma_f32_16x16x32_bf16 v[12:15], v[56:59], v[226:229], v[12:15]
	v_mfma_f32_16x16x32_bf16 v[8:11], v[138:141], v[226:229], v[8:11]
	v_mfma_f32_16x16x32_bf16 v[68:71], v[60:63], v[186:189], v[68:71]
	v_mfma_f32_16x16x32_bf16 v[64:67], v[142:145], v[186:189], v[64:67]
	v_mfma_f32_16x16x32_bf16 v[44:47], v[60:63], v[214:217], v[44:47]
	v_mfma_f32_16x16x32_bf16 v[40:43], v[142:145], v[214:217], v[40:43]
	v_mfma_f32_16x16x32_bf16 v[28:31], v[60:63], v[222:225], v[28:31]
	v_mfma_f32_16x16x32_bf16 v[24:27], v[142:145], v[222:225], v[24:27]
	v_mfma_f32_16x16x32_bf16 v[12:15], v[60:63], v[230:233], v[12:15]
	v_mfma_f32_16x16x32_bf16 v[8:11], v[142:145], v[230:233], v[8:11]
	s_setprio 0
	s_setprio 1
	v_mfma_f32_16x16x32_bf16 v[52:55], v[146:149], v[182:185], v[52:55]
	v_mfma_f32_16x16x32_bf16 v[48:51], v[154:157], v[182:185], v[48:51]
	v_mfma_f32_16x16x32_bf16 v[36:39], v[146:149], v[190:193], v[36:39]
	v_mfma_f32_16x16x32_bf16 v[32:35], v[154:157], v[190:193], v[32:35]
	v_mfma_f32_16x16x32_bf16 v[20:23], v[146:149], v[218:221], v[20:23]
	v_mfma_f32_16x16x32_bf16 v[16:19], v[154:157], v[218:221], v[16:19]
	v_mfma_f32_16x16x32_bf16 v[4:7], v[146:149], v[226:229], v[4:7]
	v_mfma_f32_16x16x32_bf16 v[0:3], v[154:157], v[226:229], v[0:3]
	v_mfma_f32_16x16x32_bf16 v[52:55], v[150:153], v[186:189], v[52:55]
	v_mfma_f32_16x16x32_bf16 v[48:51], v[170:173], v[186:189], v[48:51]
	v_mfma_f32_16x16x32_bf16 v[36:39], v[150:153], v[214:217], v[36:39]
	v_mfma_f32_16x16x32_bf16 v[32:35], v[170:173], v[214:217], v[32:35]
	v_mfma_f32_16x16x32_bf16 v[20:23], v[150:153], v[222:225], v[20:23]
	v_mfma_f32_16x16x32_bf16 v[16:19], v[170:173], v[222:225], v[16:19]
	v_mfma_f32_16x16x32_bf16 v[4:7], v[150:153], v[230:233], v[4:7]
	v_mfma_f32_16x16x32_bf16 v[0:3], v[170:173], v[230:233], v[0:3]
	s_setprio 0
	s_barrier
	s_add_i32 s2, s2, 2
	s_add_u32 s22, s22, 0x100
	s_addc_u32 s23, s23, 0
	s_add_u32 s15, s15, 0x100
	s_addc_u32 s17, s17, 0
	s_cmp_gt_u32 s2, 5
	s_cbranch_scc0 .LBB0_421
	s_nop 0
	s_nop 0
	s_nop 0
	s_nop 0
	s_and_b64 vcc, exec, s[58:59]
	s_cbranch_vccz .LBB0_424
	s_barrier

.LBB0_717:
	s_add_u32 s3, s42, 0xfffe0080
	s_addc_u32 s6, s43, -1
	s_add_i32 s7, 0, 0x10000
	s_cmp_eq_u32 s2, 4
	s_cselect_b32 s47, s23, s6
	s_cselect_b32 s46, s51, s3
	v_add_u32_e32 v140, s7, v143
	s_cselect_b32 s45, s15, s54
	s_cselect_b32 s44, s52, s53
	s_add_i32 s3, 0, 0x14000
	ds_read_b128 v[146:149], v140
	ds_read_b128 v[150:153], v140 offset:1024
	ds_read_b128 v[154:157], v140 offset:2048
	ds_read_b128 v[158:161], v140 offset:3072
	v_add_u32_e32 v140, s3, v143
	ds_read_b128 v[162:165], v140
	ds_read_b128 v[166:169], v140 offset:1024
	ds_read_b128 v[170:173], v140 offset:2048
	ds_read_b128 v[174:177], v140 offset:3072
	v_lshl_add_u64 v[140:141], s[42:43], 0, v[136:137]
	s_add_i32 m0, s20, 0xc000
	ds_read_b128 v[178:181], v145
	ds_read_b128 v[182:185], v145 offset:1024
	ds_read_b128 v[186:189], v145 offset:2048
	ds_read_b128 v[190:193], v145 offset:3072
	ds_read_b128 v[202:205], v145 offset:4096
	ds_read_b128 v[206:209], v145 offset:5120
	ds_read_b128 v[214:217], v145 offset:6144
	ds_read_b128 v[218:221], v145 offset:7168
	global_load_lds_dwordx4 v[140:141], off
	v_lshl_add_u64 v[140:141], s[42:43], 0, v[138:139]
	s_add_i32 m0, s20, 0xe000
	s_nop 0
	global_load_lds_dwordx4 v[140:141], off
	s_setprio 1
	s_waitcnt vmcnt(8)
	s_waitcnt lgkmcnt(0)
	s_barrier
	v_mfma_f32_16x16x32_bf16 v[126:129], v[146:149], v[178:181], v[126:129]
	v_mfma_f32_16x16x32_bf16 v[122:125], v[154:157], v[178:181], v[122:125]
	v_mfma_f32_16x16x32_bf16 v[118:121], v[146:149], v[186:189], v[118:121]
	v_mfma_f32_16x16x32_bf16 v[110:113], v[154:157], v[186:189], v[110:113]
	v_mfma_f32_16x16x32_bf16 v[102:105], v[146:149], v[202:205], v[102:105]
	v_mfma_f32_16x16x32_bf16 v[92:95], v[154:157], v[202:205], v[92:95]
	v_mfma_f32_16x16x32_bf16 v[84:87], v[146:149], v[214:217], v[84:87]
	v_mfma_f32_16x16x32_bf16 v[76:79], v[154:157], v[214:217], v[76:79]
	v_mfma_f32_16x16x32_bf16 v[126:129], v[150:153], v[182:185], v[126:129]
	v_mfma_f32_16x16x32_bf16 v[122:125], v[158:161], v[182:185], v[122:125]
	v_mfma_f32_16x16x32_bf16 v[118:121], v[150:153], v[190:193], v[118:121]
	v_mfma_f32_16x16x32_bf16 v[110:113], v[158:161], v[190:193], v[110:113]
	v_mfma_f32_16x16x32_bf16 v[102:105], v[150:153], v[206:209], v[102:105]
	v_mfma_f32_16x16x32_bf16 v[92:95], v[158:161], v[206:209], v[92:95]
	v_mfma_f32_16x16x32_bf16 v[84:87], v[150:153], v[218:221], v[84:87]
	v_mfma_f32_16x16x32_bf16 v[76:79], v[158:161], v[218:221], v[76:79]
	s_setprio 0
	s_setprio 1
	v_mfma_f32_16x16x32_bf16 v[114:117], v[162:165], v[178:181], v[114:117]
	v_mfma_f32_16x16x32_bf16 v[106:109], v[170:173], v[178:181], v[106:109]
	v_mfma_f32_16x16x32_bf16 v[98:101], v[162:165], v[186:189], v[98:101]
	v_mfma_f32_16x16x32_bf16 v[88:91], v[170:173], v[186:189], v[88:91]
	v_mfma_f32_16x16x32_bf16 v[80:83], v[162:165], v[202:205], v[80:83]
	v_mfma_f32_16x16x32_bf16 v[72:75], v[170:173], v[202:205], v[72:75]
	v_mfma_f32_16x16x32_bf16 v[68:71], v[162:165], v[214:217], v[68:71]
	v_mfma_f32_16x16x32_bf16 v[64:67], v[170:173], v[214:217], v[64:67]
	v_mfma_f32_16x16x32_bf16 v[114:117], v[166:169], v[182:185], v[114:117]
	v_mfma_f32_16x16x32_bf16 v[106:109], v[174:177], v[182:185], v[106:109]
	v_mfma_f32_16x16x32_bf16 v[98:101], v[166:169], v[190:193], v[98:101]
	v_mfma_f32_16x16x32_bf16 v[88:91], v[174:177], v[190:193], v[88:91]
	v_mfma_f32_16x16x32_bf16 v[80:83], v[166:169], v[206:209], v[80:83]
	v_mfma_f32_16x16x32_bf16 v[72:75], v[174:177], v[206:209], v[72:75]
	v_mfma_f32_16x16x32_bf16 v[68:71], v[166:169], v[218:221], v[68:71]
	v_mfma_f32_16x16x32_bf16 v[64:67], v[174:177], v[218:221], v[64:67]
	s_setprio 0
	s_barrier
	s_add_i32 s6, s7, s4
	v_lshl_add_u64 v[140:141], s[44:45], 0, v[96:97]
	s_mov_b32 m0, s6
	ds_read_b128 v[178:181], v145 offset:16384
	ds_read_b128 v[182:185], v145 offset:17408
	ds_read_b128 v[186:189], v145 offset:18432
	ds_read_b128 v[190:193], v145 offset:19456
	ds_read_b128 v[202:205], v145 offset:20480
	ds_read_b128 v[206:209], v145 offset:21504
	ds_read_b128 v[214:217], v145 offset:22528
	ds_read_b128 v[218:221], v145 offset:23552
	global_load_lds_dwordx4 v[140:141], off
	s_add_i32 m0, s6, 0x2000
	s_add_u32 s6, s44, 0x20000
	v_lshl_add_u64 v[194:195], s[44:45], 0, v[134:135]
	s_addc_u32 s7, s45, 0
	s_add_i32 s3, s3, s4
	global_load_lds_dwordx4 v[194:195], off
	v_lshl_add_u64 v[198:199], s[6:7], 0, v[96:97]
	s_mov_b32 m0, s3
	v_lshl_add_u64 v[200:201], s[46:47], 0, v[132:133]
	global_load_lds_dwordx4 v[198:199], off
	v_lshl_add_u64 v[198:199], s[6:7], 0, v[134:135]
	s_add_i32 m0, s3, 0x2000
	s_nop 0
	global_load_lds_dwordx4 v[198:199], off
	v_lshl_add_u64 v[198:199], s[46:47], 0, v[130:131]
	s_mov_b32 m0, s20
	s_nop 0
	global_load_lds_dwordx4 v[198:199], off
	s_mov_b32 m0, s25
	s_nop 0
	global_load_lds_dwordx4 v[200:201], off
	s_setprio 1
	s_waitcnt vmcnt(8)
	s_waitcnt lgkmcnt(0)
	s_barrier
	v_mfma_f32_16x16x32_bf16 v[60:63], v[146:149], v[178:181], v[60:63]
	v_mfma_f32_16x16x32_bf16 v[56:59], v[154:157], v[178:181], v[56:59]
	v_mfma_f32_16x16x32_bf16 v[52:55], v[146:149], v[186:189], v[52:55]
	v_mfma_f32_16x16x32_bf16 v[44:47], v[154:157], v[186:189], v[44:47]
	v_mfma_f32_16x16x32_bf16 v[36:39], v[146:149], v[202:205], v[36:39]
	v_mfma_f32_16x16x32_bf16 v[28:31], v[154:157], v[202:205], v[28:31]
	v_mfma_f32_16x16x32_bf16 v[20:23], v[146:149], v[214:217], v[20:23]
	v_mfma_f32_16x16x32_bf16 v[12:15], v[154:157], v[214:217], v[12:15]
	v_mfma_f32_16x16x32_bf16 v[60:63], v[150:153], v[182:185], v[60:63]
	v_mfma_f32_16x16x32_bf16 v[56:59], v[158:161], v[182:185], v[56:59]
	v_mfma_f32_16x16x32_bf16 v[52:55], v[150:153], v[190:193], v[52:55]
	v_mfma_f32_16x16x32_bf16 v[44:47], v[158:161], v[190:193], v[44:47]
	v_mfma_f32_16x16x32_bf16 v[36:39], v[150:153], v[206:209], v[36:39]
	v_mfma_f32_16x16x32_bf16 v[28:31], v[158:161], v[206:209], v[28:31]
	v_mfma_f32_16x16x32_bf16 v[20:23], v[150:153], v[218:221], v[20:23]
	v_mfma_f32_16x16x32_bf16 v[12:15], v[158:161], v[218:221], v[12:15]
	s_setprio 0
	s_setprio 1
	v_mfma_f32_16x16x32_bf16 v[48:51], v[162:165], v[178:181], v[48:51]
	v_mfma_f32_16x16x32_bf16 v[40:43], v[170:173], v[178:181], v[40:43]
	v_mfma_f32_16x16x32_bf16 v[32:35], v[162:165], v[186:189], v[32:35]
	v_mfma_f32_16x16x32_bf16 v[24:27], v[170:173], v[186:189], v[24:27]
	v_mfma_f32_16x16x32_bf16 v[16:19], v[162:165], v[202:205], v[16:19]
	v_mfma_f32_16x16x32_bf16 v[8:11], v[170:173], v[202:205], v[8:11]
	v_mfma_f32_16x16x32_bf16 v[4:7], v[162:165], v[214:217], v[4:7]
	v_mfma_f32_16x16x32_bf16 v[0:3], v[170:173], v[214:217], v[0:3]
	v_mfma_f32_16x16x32_bf16 v[48:51], v[166:169], v[182:185], v[48:51]
	v_mfma_f32_16x16x32_bf16 v[40:43], v[174:177], v[182:185], v[40:43]
	v_mfma_f32_16x16x32_bf16 v[32:35], v[166:169], v[190:193], v[32:35]
	v_mfma_f32_16x16x32_bf16 v[24:27], v[174:177], v[190:193], v[24:27]
	v_mfma_f32_16x16x32_bf16 v[16:19], v[166:169], v[206:209], v[16:19]
	v_mfma_f32_16x16x32_bf16 v[8:11], v[174:177], v[206:209], v[8:11]
	v_mfma_f32_16x16x32_bf16 v[4:7], v[166:169], v[218:221], v[4:7]
	v_mfma_f32_16x16x32_bf16 v[0:3], v[174:177], v[218:221], v[0:3]
	s_setprio 0
	s_barrier
	s_add_i32 s3, 0, 0x18000
	s_add_i32 s55, 0, 0x1c000
	v_add_u32_e32 v158, s3, v143
	v_add_u32_e32 v174, s55, v143
	ds_read_b128 v[146:149], v158
	ds_read_b128 v[150:153], v158 offset:1024
	ds_read_b128 v[154:157], v158 offset:2048
	ds_read_b128 v[158:161], v158 offset:3072
	ds_read_b128 v[162:165], v174
	ds_read_b128 v[166:169], v174 offset:1024
	ds_read_b128 v[170:173], v174 offset:2048
	ds_read_b128 v[174:177], v174 offset:3072
	s_add_u32 s6, s46, 0x20000
	s_addc_u32 s7, s47, 0
	s_mov_b32 m0, s36
	v_lshl_add_u64 v[222:223], s[6:7], 0, v[130:131]
	ds_read_b128 v[178:181], v145 offset:32768
	ds_read_b128 v[182:185], v145 offset:33792
	ds_read_b128 v[186:189], v145 offset:34816
	ds_read_b128 v[190:193], v145 offset:35840
	ds_read_b128 v[202:205], v145 offset:36864
	ds_read_b128 v[206:209], v145 offset:37888
	ds_read_b128 v[214:217], v145 offset:38912
	ds_read_b128 v[218:221], v145 offset:39936
	global_load_lds_dwordx4 v[222:223], off
	v_lshl_add_u64 v[222:223], s[6:7], 0, v[132:133]
	s_mov_b32 m0, s37
	s_nop 0
	global_load_lds_dwordx4 v[222:223], off
	s_setprio 1
	s_waitcnt vmcnt(8)
	s_waitcnt lgkmcnt(0)
	s_barrier
	v_mfma_f32_16x16x32_bf16 v[126:129], v[146:149], v[178:181], v[126:129]
	v_mfma_f32_16x16x32_bf16 v[122:125], v[154:157], v[178:181], v[122:125]
	v_mfma_f32_16x16x32_bf16 v[118:121], v[146:149], v[186:189], v[118:121]
	v_mfma_f32_16x16x32_bf16 v[110:113], v[154:157], v[186:189], v[110:113]
	v_mfma_f32_16x16x32_bf16 v[102:105], v[146:149], v[202:205], v[102:105]
	v_mfma_f32_16x16x32_bf16 v[92:95], v[154:157], v[202:205], v[92:95]
	v_mfma_f32_16x16x32_bf16 v[84:87], v[146:149], v[214:217], v[84:87]
	v_mfma_f32_16x16x32_bf16 v[76:79], v[154:157], v[214:217], v[76:79]
	v_mfma_f32_16x16x32_bf16 v[126:129], v[150:153], v[182:185], v[126:129]
	v_mfma_f32_16x16x32_bf16 v[122:125], v[158:161], v[182:185], v[122:125]
	v_mfma_f32_16x16x32_bf16 v[118:121], v[150:153], v[190:193], v[118:121]
	v_mfma_f32_16x16x32_bf16 v[110:113], v[158:161], v[190:193], v[110:113]
	v_mfma_f32_16x16x32_bf16 v[102:105], v[150:153], v[206:209], v[102:105]
	v_mfma_f32_16x16x32_bf16 v[92:95], v[158:161], v[206:209], v[92:95]
	v_mfma_f32_16x16x32_bf16 v[84:87], v[150:153], v[218:221], v[84:87]
	v_mfma_f32_16x16x32_bf16 v[76:79], v[158:161], v[218:221], v[76:79]
	s_setprio 0
	s_setprio 1
	v_mfma_f32_16x16x32_bf16 v[114:117], v[162:165], v[178:181], v[114:117]
	v_mfma_f32_16x16x32_bf16 v[106:109], v[170:173], v[178:181], v[106:109]
	v_mfma_f32_16x16x32_bf16 v[98:101], v[162:165], v[186:189], v[98:101]
	v_mfma_f32_16x16x32_bf16 v[88:91], v[170:173], v[186:189], v[88:91]
	v_mfma_f32_16x16x32_bf16 v[80:83], v[162:165], v[202:205], v[80:83]
	v_mfma_f32_16x16x32_bf16 v[72:75], v[170:173], v[202:205], v[72:75]
	v_mfma_f32_16x16x32_bf16 v[68:71], v[162:165], v[214:217], v[68:71]
	v_mfma_f32_16x16x32_bf16 v[64:67], v[170:173], v[214:217], v[64:67]
	v_mfma_f32_16x16x32_bf16 v[114:117], v[166:169], v[182:185], v[114:117]
	v_mfma_f32_16x16x32_bf16 v[106:109], v[174:177], v[182:185], v[106:109]
	v_mfma_f32_16x16x32_bf16 v[98:101], v[166:169], v[190:193], v[98:101]
	v_mfma_f32_16x16x32_bf16 v[88:91], v[174:177], v[190:193], v[88:91]
	v_mfma_f32_16x16x32_bf16 v[80:83], v[166:169], v[206:209], v[80:83]
	v_mfma_f32_16x16x32_bf16 v[72:75], v[174:177], v[206:209], v[72:75]
	v_mfma_f32_16x16x32_bf16 v[68:71], v[166:169], v[218:221], v[68:71]
	v_mfma_f32_16x16x32_bf16 v[64:67], v[174:177], v[218:221], v[64:67]
	s_setprio 0
	s_barrier
	s_add_i32 s3, s3, s4
	v_lshl_add_u64 v[140:141], v[140:141], 0, s[30:31]
	s_mov_b32 m0, s3
	ds_read_b128 v[178:181], v145 offset:49152
	ds_read_b128 v[182:185], v145 offset:50176
	ds_read_b128 v[186:189], v145 offset:51200
	ds_read_b128 v[190:193], v145 offset:52224
	ds_read_b128 v[202:205], v145 offset:53248
	ds_read_b128 v[206:209], v145 offset:54272
	ds_read_b128 v[214:217], v145 offset:55296
	ds_read_b128 v[218:221], v145 offset:56320
	global_load_lds_dwordx4 v[140:141], off
	s_add_i32 m0, s3, 0x2000
	s_add_u32 s6, s44, 0x20080
	v_lshl_add_u64 v[140:141], v[194:195], 0, s[30:31]
	s_addc_u32 s7, s45, 0
	s_add_i32 s3, s55, s4
	global_load_lds_dwordx4 v[140:141], off
	v_lshl_add_u64 v[140:141], s[6:7], 0, v[96:97]
	s_mov_b32 m0, s3
	s_nop 0
	global_load_lds_dwordx4 v[140:141], off
	v_lshl_add_u64 v[140:141], s[6:7], 0, v[134:135]
	s_add_i32 m0, s3, 0x2000
	s_nop 0
	global_load_lds_dwordx4 v[140:141], off
	v_lshl_add_u64 v[140:141], v[198:199], 0, s[30:31]
	s_mov_b32 m0, s40
	s_nop 0
	global_load_lds_dwordx4 v[140:141], off
	v_lshl_add_u64 v[140:141], v[200:201], 0, s[30:31]
	s_mov_b32 m0, s48
	s_nop 0
	global_load_lds_dwordx4 v[140:141], off
	s_setprio 1
	s_waitcnt vmcnt(8)
	s_waitcnt lgkmcnt(0)
	s_barrier
	v_mfma_f32_16x16x32_bf16 v[60:63], v[146:149], v[178:181], v[60:63]
	v_mfma_f32_16x16x32_bf16 v[56:59], v[154:157], v[178:181], v[56:59]
	v_mfma_f32_16x16x32_bf16 v[52:55], v[146:149], v[186:189], v[52:55]
	v_mfma_f32_16x16x32_bf16 v[44:47], v[154:157], v[186:189], v[44:47]
	v_mfma_f32_16x16x32_bf16 v[36:39], v[146:149], v[202:205], v[36:39]
	v_mfma_f32_16x16x32_bf16 v[28:31], v[154:157], v[202:205], v[28:31]
	v_mfma_f32_16x16x32_bf16 v[20:23], v[146:149], v[214:217], v[20:23]
	v_mfma_f32_16x16x32_bf16 v[12:15], v[154:157], v[214:217], v[12:15]
	v_mfma_f32_16x16x32_bf16 v[60:63], v[150:153], v[182:185], v[60:63]
	v_mfma_f32_16x16x32_bf16 v[56:59], v[158:161], v[182:185], v[56:59]
	v_mfma_f32_16x16x32_bf16 v[52:55], v[150:153], v[190:193], v[52:55]
	v_mfma_f32_16x16x32_bf16 v[44:47], v[158:161], v[190:193], v[44:47]
	v_mfma_f32_16x16x32_bf16 v[36:39], v[150:153], v[206:209], v[36:39]
	v_mfma_f32_16x16x32_bf16 v[28:31], v[158:161], v[206:209], v[28:31]
	v_mfma_f32_16x16x32_bf16 v[20:23], v[150:153], v[218:221], v[20:23]
	v_mfma_f32_16x16x32_bf16 v[12:15], v[158:161], v[218:221], v[12:15]
	s_setprio 0
	s_setprio 1
	v_mfma_f32_16x16x32_bf16 v[48:51], v[162:165], v[178:181], v[48:51]
	v_mfma_f32_16x16x32_bf16 v[40:43], v[170:173], v[178:181], v[40:43]
	v_mfma_f32_16x16x32_bf16 v[32:35], v[162:165], v[186:189], v[32:35]
	v_mfma_f32_16x16x32_bf16 v[24:27], v[170:173], v[186:189], v[24:27]
	v_mfma_f32_16x16x32_bf16 v[16:19], v[162:165], v[202:205], v[16:19]
	v_mfma_f32_16x16x32_bf16 v[8:11], v[170:173], v[202:205], v[8:11]
	v_mfma_f32_16x16x32_bf16 v[4:7], v[162:165], v[214:217], v[4:7]
	v_mfma_f32_16x16x32_bf16 v[0:3], v[170:173], v[214:217], v[0:3]
	v_mfma_f32_16x16x32_bf16 v[48:51], v[166:169], v[182:185], v[48:51]
	v_mfma_f32_16x16x32_bf16 v[40:43], v[174:177], v[182:185], v[40:43]
	v_mfma_f32_16x16x32_bf16 v[32:35], v[166:169], v[190:193], v[32:35]
	v_mfma_f32_16x16x32_bf16 v[24:27], v[174:177], v[190:193], v[24:27]
	v_mfma_f32_16x16x32_bf16 v[16:19], v[166:169], v[206:209], v[16:19]
	v_mfma_f32_16x16x32_bf16 v[8:11], v[174:177], v[206:209], v[8:11]
	v_mfma_f32_16x16x32_bf16 v[4:7], v[166:169], v[218:221], v[4:7]
	v_mfma_f32_16x16x32_bf16 v[0:3], v[174:177], v[218:221], v[0:3]
	s_setprio 0
	s_barrier
	s_add_i32 s2, s2, 2
	s_add_u32 s42, s42, 0x100
	s_addc_u32 s43, s43, 0
	s_add_u32 s53, s53, 0x100
	s_addc_u32 s54, s54, 0
	s_cmp_gt_u32 s2, 5
	s_cbranch_scc0 .LBB0_717
	s_nop 0
	s_nop 0
	s_nop 0
	s_nop 0
	v_readlane_b32 s54, v254, 56
	s_and_b64 vcc, exec, s[10:11]
	v_readlane_b32 s55, v254, 57
	s_cbranch_vccz .LBB0_720
	s_barrier

.LBB0_993:
	s_add_u32 s3, s24, s46
	s_addc_u32 s6, s25, s47
	s_add_u32 s3, s3, 0x100
	s_addc_u32 s6, s6, 0
	s_add_u32 s48, s59, s46
	s_addc_u32 s49, s60, s47
	s_add_i32 s63, 0, 0x10000
	s_cmpk_eq_i32 s46, 0xf00
	s_cselect_b32 s51, s23, s6
	s_cselect_b32 s50, s61, s3
	v_add_u32_e32 v146, s63, v144
	s_cselect_b32 s49, s15, s49
	s_cselect_b32 s48, s62, s48
	s_add_i32 s3, 0, 0x14000
	ds_read_b128 v[154:157], v146
	ds_read_b128 v[158:161], v146 offset:1024
	ds_read_b128 v[162:165], v146 offset:2048
	ds_read_b128 v[166:169], v146 offset:3072
	v_add_u32_e32 v146, s3, v144
	ds_read_b128 v[174:177], v146
	ds_read_b128 v[178:181], v146 offset:1024
	ds_read_b128 v[182:185], v146 offset:2048
	ds_read_b128 v[186:189], v146 offset:3072
	v_lshl_add_u64 v[146:147], v[140:141], 0, s[46:47]
	s_add_i32 m0, s17, 0xc000
	ds_read_b128 v[190:193], v145
	ds_read_b128 v[202:205], v145 offset:1024
	ds_read_b128 v[206:209], v145 offset:2048
	ds_read_b128 v[214:217], v145 offset:3072
	ds_read_b128 v[218:221], v145 offset:4096
	ds_read_b128 v[222:225], v145 offset:5120
	ds_read_b128 v[226:229], v145 offset:6144
	ds_read_b128 v[230:233], v145 offset:7168
	global_load_lds_dwordx4 v[146:147], off
	v_lshl_add_u64 v[146:147], v[142:143], 0, s[46:47]
	s_add_i32 m0, s17, 0xe000
	s_nop 0
	global_load_lds_dwordx4 v[146:147], off
	s_setprio 1
	s_waitcnt vmcnt(8)
	s_waitcnt lgkmcnt(0)
	s_barrier
	v_mfma_f32_16x16x32_bf16 v[110:113], v[154:157], v[190:193], v[110:113]
	v_mfma_f32_16x16x32_bf16 v[106:109], v[162:165], v[190:193], v[106:109]
	v_mfma_f32_16x16x32_bf16 v[118:121], v[154:157], v[206:209], v[118:121]
	v_mfma_f32_16x16x32_bf16 v[114:117], v[162:165], v[206:209], v[114:117]
	v_mfma_f32_16x16x32_bf16 v[126:129], v[154:157], v[218:221], v[126:129]
	v_mfma_f32_16x16x32_bf16 v[122:125], v[162:165], v[218:221], v[122:125]
	v_mfma_f32_16x16x32_bf16 v[92:95], v[154:157], v[226:229], v[92:95]
	v_mfma_f32_16x16x32_bf16 v[88:91], v[162:165], v[226:229], v[88:91]
	v_mfma_f32_16x16x32_bf16 v[110:113], v[158:161], v[202:205], v[110:113]
	v_mfma_f32_16x16x32_bf16 v[106:109], v[166:169], v[202:205], v[106:109]
	v_mfma_f32_16x16x32_bf16 v[118:121], v[158:161], v[214:217], v[118:121]
	v_mfma_f32_16x16x32_bf16 v[114:117], v[166:169], v[214:217], v[114:117]
	v_mfma_f32_16x16x32_bf16 v[126:129], v[158:161], v[222:225], v[126:129]
	v_mfma_f32_16x16x32_bf16 v[122:125], v[166:169], v[222:225], v[122:125]
	v_mfma_f32_16x16x32_bf16 v[92:95], v[158:161], v[230:233], v[92:95]
	v_mfma_f32_16x16x32_bf16 v[88:91], v[166:169], v[230:233], v[88:91]
	s_setprio 0
	s_setprio 1
	v_mfma_f32_16x16x32_bf16 v[4:7], v[174:177], v[190:193], v[4:7]
	v_mfma_f32_16x16x32_bf16 v[0:3], v[182:185], v[190:193], v[0:3]
	v_mfma_f32_16x16x32_bf16 v[12:15], v[174:177], v[206:209], v[12:15]
	v_mfma_f32_16x16x32_bf16 v[8:11], v[182:185], v[206:209], v[8:11]
	v_mfma_f32_16x16x32_bf16 v[24:27], v[174:177], v[218:221], v[24:27]
	v_mfma_f32_16x16x32_bf16 v[20:23], v[182:185], v[218:221], v[20:23]
	v_mfma_f32_16x16x32_bf16 v[40:43], v[174:177], v[226:229], v[40:43]
	v_mfma_f32_16x16x32_bf16 v[32:35], v[182:185], v[226:229], v[32:35]
	v_mfma_f32_16x16x32_bf16 v[4:7], v[178:181], v[202:205], v[4:7]
	v_mfma_f32_16x16x32_bf16 v[0:3], v[186:189], v[202:205], v[0:3]
	v_mfma_f32_16x16x32_bf16 v[12:15], v[178:181], v[214:217], v[12:15]
	v_mfma_f32_16x16x32_bf16 v[8:11], v[186:189], v[214:217], v[8:11]
	v_mfma_f32_16x16x32_bf16 v[24:27], v[178:181], v[222:225], v[24:27]
	v_mfma_f32_16x16x32_bf16 v[20:23], v[186:189], v[222:225], v[20:23]
	v_mfma_f32_16x16x32_bf16 v[40:43], v[178:181], v[230:233], v[40:43]
	v_mfma_f32_16x16x32_bf16 v[32:35], v[186:189], v[230:233], v[32:35]
	s_setprio 0
	s_barrier
	s_add_i32 s6, s63, s5
	v_lshl_add_u64 v[146:147], s[48:49], 0, v[96:97]
	s_mov_b32 m0, s6
	ds_read_b128 v[190:193], v145 offset:16384
	ds_read_b128 v[202:205], v145 offset:17408
	ds_read_b128 v[206:209], v145 offset:18432
	ds_read_b128 v[214:217], v145 offset:19456
	ds_read_b128 v[218:221], v145 offset:20480
	ds_read_b128 v[222:225], v145 offset:21504
	ds_read_b128 v[226:229], v145 offset:22528
	ds_read_b128 v[230:233], v145 offset:23552
	global_load_lds_dwordx4 v[146:147], off
	s_add_i32 m0, s6, 0x2000
	s_add_u32 s72, s48, 0x80000
	v_lshl_add_u64 v[150:151], s[48:49], 0, v[130:131]
	s_addc_u32 s73, s49, 0
	s_add_i32 s3, s3, s5
	global_load_lds_dwordx4 v[150:151], off
	v_lshl_add_u64 v[170:171], s[72:73], 0, v[96:97]
	s_mov_b32 m0, s3
	v_lshl_add_u64 v[194:195], s[50:51], 0, v[132:133]
	global_load_lds_dwordx4 v[170:171], off
	v_lshl_add_u64 v[170:171], s[72:73], 0, v[130:131]
	s_add_i32 m0, s3, 0x2000
	s_nop 0
	global_load_lds_dwordx4 v[170:171], off
	v_lshl_add_u64 v[170:171], s[50:51], 0, v[134:135]
	s_mov_b32 m0, s17
	s_nop 0
	global_load_lds_dwordx4 v[170:171], off
	s_mov_b32 m0, s18
	s_nop 0
	global_load_lds_dwordx4 v[194:195], off
	s_setprio 1
	s_waitcnt vmcnt(8)
	s_waitcnt lgkmcnt(0)
	s_barrier
	v_mfma_f32_16x16x32_bf16 v[102:105], v[154:157], v[190:193], v[102:105]
	v_mfma_f32_16x16x32_bf16 v[98:101], v[162:165], v[190:193], v[98:101]
	v_mfma_f32_16x16x32_bf16 v[84:87], v[154:157], v[206:209], v[84:87]
	v_mfma_f32_16x16x32_bf16 v[80:83], v[162:165], v[206:209], v[80:83]
	v_mfma_f32_16x16x32_bf16 v[68:71], v[154:157], v[218:221], v[68:71]
	v_mfma_f32_16x16x32_bf16 v[64:67], v[162:165], v[218:221], v[64:67]
	v_mfma_f32_16x16x32_bf16 v[44:47], v[154:157], v[226:229], v[44:47]
	v_mfma_f32_16x16x32_bf16 v[36:39], v[162:165], v[226:229], v[36:39]
	v_mfma_f32_16x16x32_bf16 v[102:105], v[158:161], v[202:205], v[102:105]
	v_mfma_f32_16x16x32_bf16 v[98:101], v[166:169], v[202:205], v[98:101]
	v_mfma_f32_16x16x32_bf16 v[84:87], v[158:161], v[214:217], v[84:87]
	v_mfma_f32_16x16x32_bf16 v[80:83], v[166:169], v[214:217], v[80:83]
	v_mfma_f32_16x16x32_bf16 v[68:71], v[158:161], v[222:225], v[68:71]
	v_mfma_f32_16x16x32_bf16 v[64:67], v[166:169], v[222:225], v[64:67]
	v_mfma_f32_16x16x32_bf16 v[44:47], v[158:161], v[230:233], v[44:47]
	v_mfma_f32_16x16x32_bf16 v[36:39], v[166:169], v[230:233], v[36:39]
	s_setprio 0
	s_setprio 1
	v_mfma_f32_16x16x32_bf16 v[60:63], v[174:177], v[190:193], v[60:63]
	v_mfma_f32_16x16x32_bf16 v[56:59], v[182:185], v[190:193], v[56:59]
	v_mfma_f32_16x16x32_bf16 v[76:79], v[174:177], v[206:209], v[76:79]
	v_mfma_f32_16x16x32_bf16 v[72:75], v[182:185], v[206:209], v[72:75]
	v_mfma_f32_16x16x32_bf16 v[52:55], v[174:177], v[218:221], v[52:55]
	v_mfma_f32_16x16x32_bf16 v[48:51], v[182:185], v[218:221], v[48:51]
	v_mfma_f32_16x16x32_bf16 v[28:31], v[174:177], v[226:229], v[28:31]
	v_mfma_f32_16x16x32_bf16 v[16:19], v[182:185], v[226:229], v[16:19]
	v_mfma_f32_16x16x32_bf16 v[60:63], v[178:181], v[202:205], v[60:63]
	v_mfma_f32_16x16x32_bf16 v[56:59], v[186:189], v[202:205], v[56:59]
	v_mfma_f32_16x16x32_bf16 v[76:79], v[178:181], v[214:217], v[76:79]
	v_mfma_f32_16x16x32_bf16 v[72:75], v[186:189], v[214:217], v[72:75]
	v_mfma_f32_16x16x32_bf16 v[52:55], v[178:181], v[222:225], v[52:55]
	v_mfma_f32_16x16x32_bf16 v[48:51], v[186:189], v[222:225], v[48:51]
	v_mfma_f32_16x16x32_bf16 v[28:31], v[178:181], v[230:233], v[28:31]
	v_mfma_f32_16x16x32_bf16 v[16:19], v[186:189], v[230:233], v[16:19]
	s_setprio 0
	s_barrier
	s_add_i32 s3, 0, 0x18000
	v_add_u32_e32 v149, s3, v144
	s_add_i32 s6, 0, 0x1c000
	ds_read_b128 v[154:157], v149
	ds_read_b128 v[158:161], v149 offset:1024
	ds_read_b128 v[162:165], v149 offset:2048
	ds_read_b128 v[166:169], v149 offset:3072
	v_add_u32_e32 v149, s6, v144
	ds_read_b128 v[174:177], v149
	ds_read_b128 v[178:181], v149 offset:1024
	ds_read_b128 v[182:185], v149 offset:2048
	ds_read_b128 v[186:189], v149 offset:3072
	s_add_u32 s50, s50, 0x80000
	s_addc_u32 s51, s51, 0
	s_mov_b32 m0, s19
	v_lshl_add_u64 v[198:199], s[50:51], 0, v[134:135]
	ds_read_b128 v[190:193], v145 offset:32768
	ds_read_b128 v[202:205], v145 offset:33792
	ds_read_b128 v[206:209], v145 offset:34816
	ds_read_b128 v[214:217], v145 offset:35840
	ds_read_b128 v[218:221], v145 offset:36864
	ds_read_b128 v[222:225], v145 offset:37888
	ds_read_b128 v[226:229], v145 offset:38912
	ds_read_b128 v[230:233], v145 offset:39936
	global_load_lds_dwordx4 v[198:199], off
	v_lshl_add_u64 v[198:199], s[50:51], 0, v[132:133]
	s_mov_b32 m0, s20
	s_nop 0
	global_load_lds_dwordx4 v[198:199], off
	s_setprio 1
	s_waitcnt vmcnt(8)
	s_waitcnt lgkmcnt(0)
	s_barrier
	v_mfma_f32_16x16x32_bf16 v[110:113], v[154:157], v[190:193], v[110:113]
	v_mfma_f32_16x16x32_bf16 v[106:109], v[162:165], v[190:193], v[106:109]
	v_mfma_f32_16x16x32_bf16 v[118:121], v[154:157], v[206:209], v[118:121]
	v_mfma_f32_16x16x32_bf16 v[114:117], v[162:165], v[206:209], v[114:117]
	v_mfma_f32_16x16x32_bf16 v[126:129], v[154:157], v[218:221], v[126:129]
	v_mfma_f32_16x16x32_bf16 v[122:125], v[162:165], v[218:221], v[122:125]
	v_mfma_f32_16x16x32_bf16 v[92:95], v[154:157], v[226:229], v[92:95]
	v_mfma_f32_16x16x32_bf16 v[88:91], v[162:165], v[226:229], v[88:91]
	v_mfma_f32_16x16x32_bf16 v[110:113], v[158:161], v[202:205], v[110:113]
	v_mfma_f32_16x16x32_bf16 v[106:109], v[166:169], v[202:205], v[106:109]
	v_mfma_f32_16x16x32_bf16 v[118:121], v[158:161], v[214:217], v[118:121]
	v_mfma_f32_16x16x32_bf16 v[114:117], v[166:169], v[214:217], v[114:117]
	v_mfma_f32_16x16x32_bf16 v[126:129], v[158:161], v[222:225], v[126:129]
	v_mfma_f32_16x16x32_bf16 v[122:125], v[166:169], v[222:225], v[122:125]
	v_mfma_f32_16x16x32_bf16 v[92:95], v[158:161], v[230:233], v[92:95]
	v_mfma_f32_16x16x32_bf16 v[88:91], v[166:169], v[230:233], v[88:91]
	s_setprio 0
	s_setprio 1
	v_mfma_f32_16x16x32_bf16 v[4:7], v[174:177], v[190:193], v[4:7]
	v_mfma_f32_16x16x32_bf16 v[0:3], v[182:185], v[190:193], v[0:3]
	v_mfma_f32_16x16x32_bf16 v[12:15], v[174:177], v[206:209], v[12:15]
	v_mfma_f32_16x16x32_bf16 v[8:11], v[182:185], v[206:209], v[8:11]
	v_mfma_f32_16x16x32_bf16 v[24:27], v[174:177], v[218:221], v[24:27]
	v_mfma_f32_16x16x32_bf16 v[20:23], v[182:185], v[218:221], v[20:23]
	v_mfma_f32_16x16x32_bf16 v[40:43], v[174:177], v[226:229], v[40:43]
	v_mfma_f32_16x16x32_bf16 v[32:35], v[182:185], v[226:229], v[32:35]
	v_mfma_f32_16x16x32_bf16 v[4:7], v[178:181], v[202:205], v[4:7]
	v_mfma_f32_16x16x32_bf16 v[0:3], v[186:189], v[202:205], v[0:3]
	v_mfma_f32_16x16x32_bf16 v[12:15], v[178:181], v[214:217], v[12:15]
	v_mfma_f32_16x16x32_bf16 v[8:11], v[186:189], v[214:217], v[8:11]
	v_mfma_f32_16x16x32_bf16 v[24:27], v[178:181], v[222:225], v[24:27]
	v_mfma_f32_16x16x32_bf16 v[20:23], v[186:189], v[222:225], v[20:23]
	v_mfma_f32_16x16x32_bf16 v[40:43], v[178:181], v[230:233], v[40:43]
	v_mfma_f32_16x16x32_bf16 v[32:35], v[186:189], v[230:233], v[32:35]
	s_setprio 0
	s_barrier
	s_add_i32 s3, s3, s5
	v_lshl_add_u64 v[146:147], v[146:147], 0, s[30:31]
	s_mov_b32 m0, s3
	ds_read_b128 v[190:193], v145 offset:49152
	ds_read_b128 v[202:205], v145 offset:50176
	ds_read_b128 v[206:209], v145 offset:51200
	ds_read_b128 v[214:217], v145 offset:52224
	ds_read_b128 v[218:221], v145 offset:53248
	ds_read_b128 v[222:225], v145 offset:54272
	ds_read_b128 v[226:229], v145 offset:55296
	ds_read_b128 v[230:233], v145 offset:56320
	global_load_lds_dwordx4 v[146:147], off
	s_add_i32 m0, s3, 0x2000
	s_add_u32 s48, s48, 0x80080
	v_lshl_add_u64 v[146:147], v[150:151], 0, s[30:31]
	s_addc_u32 s49, s49, 0
	s_add_i32 s3, s6, s5
	global_load_lds_dwordx4 v[146:147], off
	v_lshl_add_u64 v[146:147], s[48:49], 0, v[96:97]
	s_mov_b32 m0, s3
	s_nop 0
	global_load_lds_dwordx4 v[146:147], off
	v_lshl_add_u64 v[146:147], s[48:49], 0, v[130:131]
	s_add_i32 m0, s3, 0x2000
	s_nop 0
	global_load_lds_dwordx4 v[146:147], off
	v_lshl_add_u64 v[146:147], v[170:171], 0, s[30:31]
	s_mov_b32 m0, s37
	s_nop 0
	global_load_lds_dwordx4 v[146:147], off
	v_lshl_add_u64 v[146:147], v[194:195], 0, s[30:31]
	s_mov_b32 m0, s56
	s_nop 0
	global_load_lds_dwordx4 v[146:147], off
	s_setprio 1
	s_waitcnt vmcnt(8)
	s_waitcnt lgkmcnt(0)
	s_barrier
	v_mfma_f32_16x16x32_bf16 v[102:105], v[154:157], v[190:193], v[102:105]
	v_mfma_f32_16x16x32_bf16 v[98:101], v[162:165], v[190:193], v[98:101]
	v_mfma_f32_16x16x32_bf16 v[84:87], v[154:157], v[206:209], v[84:87]
	v_mfma_f32_16x16x32_bf16 v[80:83], v[162:165], v[206:209], v[80:83]
	v_mfma_f32_16x16x32_bf16 v[68:71], v[154:157], v[218:221], v[68:71]
	v_mfma_f32_16x16x32_bf16 v[64:67], v[162:165], v[218:221], v[64:67]
	v_mfma_f32_16x16x32_bf16 v[44:47], v[154:157], v[226:229], v[44:47]
	v_mfma_f32_16x16x32_bf16 v[36:39], v[162:165], v[226:229], v[36:39]
	v_mfma_f32_16x16x32_bf16 v[102:105], v[158:161], v[202:205], v[102:105]
	v_mfma_f32_16x16x32_bf16 v[98:101], v[166:169], v[202:205], v[98:101]
	v_mfma_f32_16x16x32_bf16 v[84:87], v[158:161], v[214:217], v[84:87]
	v_mfma_f32_16x16x32_bf16 v[80:83], v[166:169], v[214:217], v[80:83]
	v_mfma_f32_16x16x32_bf16 v[68:71], v[158:161], v[222:225], v[68:71]
	v_mfma_f32_16x16x32_bf16 v[64:67], v[166:169], v[222:225], v[64:67]
	v_mfma_f32_16x16x32_bf16 v[44:47], v[158:161], v[230:233], v[44:47]
	v_mfma_f32_16x16x32_bf16 v[36:39], v[166:169], v[230:233], v[36:39]
	s_setprio 0
	s_setprio 1
	v_mfma_f32_16x16x32_bf16 v[60:63], v[174:177], v[190:193], v[60:63]
	v_mfma_f32_16x16x32_bf16 v[56:59], v[182:185], v[190:193], v[56:59]
	v_mfma_f32_16x16x32_bf16 v[76:79], v[174:177], v[206:209], v[76:79]
	v_mfma_f32_16x16x32_bf16 v[72:75], v[182:185], v[206:209], v[72:75]
	v_mfma_f32_16x16x32_bf16 v[52:55], v[174:177], v[218:221], v[52:55]
	v_mfma_f32_16x16x32_bf16 v[48:51], v[182:185], v[218:221], v[48:51]
	v_mfma_f32_16x16x32_bf16 v[28:31], v[174:177], v[226:229], v[28:31]
	v_mfma_f32_16x16x32_bf16 v[16:19], v[182:185], v[226:229], v[16:19]
	v_mfma_f32_16x16x32_bf16 v[60:63], v[178:181], v[202:205], v[60:63]
	v_mfma_f32_16x16x32_bf16 v[56:59], v[186:189], v[202:205], v[56:59]
	v_mfma_f32_16x16x32_bf16 v[76:79], v[178:181], v[214:217], v[76:79]
	v_mfma_f32_16x16x32_bf16 v[72:75], v[186:189], v[214:217], v[72:75]
	v_mfma_f32_16x16x32_bf16 v[52:55], v[178:181], v[222:225], v[52:55]
	v_mfma_f32_16x16x32_bf16 v[48:51], v[186:189], v[222:225], v[48:51]
	v_mfma_f32_16x16x32_bf16 v[28:31], v[178:181], v[230:233], v[28:31]
	v_mfma_f32_16x16x32_bf16 v[16:19], v[186:189], v[230:233], v[16:19]
	s_setprio 0
	s_barrier
	s_add_i32 s2, s2, 2
	s_add_u32 s46, s46, 0x100
	s_addc_u32 s47, s47, 0
	s_cmp_gt_u32 s2, 29
	s_cbranch_scc0 .LBB0_993
	s_nop 0
	s_nop 0
	s_nop 0
	s_nop 0
	s_and_b64 vcc, exec, s[12:13]
	s_cbranch_vccz .LBB0_996
	s_barrier

.LBB0_1158:
	s_add_u32 s34, s62, 0x100
	s_addc_u32 s35, s63, 0
	s_add_i32 s67, 0, 0x10000
	s_cmp_eq_u32 s6, 28
	s_cselect_b32 s89, s23, s35
	s_cselect_b32 s88, s61, s34
	s_cselect_b32 vcc_hi, s91, s3
	s_cselect_b32 vcc_lo, s93, s2
	s_add_i32 s76, 0, 0x14000
	v_add_u32_e32 v142, s67, v191
	v_add_u32_e32 v158, s76, v191
	ds_read_b128 v[130:133], v142
	ds_read_b128 v[134:137], v142 offset:1024
	ds_read_b128 v[138:141], v142 offset:2048
	ds_read_b128 v[142:145], v142 offset:3072
	ds_read_b128 v[146:149], v158
	ds_read_b128 v[150:153], v158 offset:1024
	ds_read_b128 v[154:157], v158 offset:2048
	ds_read_b128 v[158:161], v158 offset:3072
	v_lshl_add_u64 v[188:189], s[62:63], 0, v[184:185]
	s_add_i32 m0, s17, 0xc000
	ds_read_b128 v[162:165], v224
	ds_read_b128 v[166:169], v224 offset:1024
	ds_read_b128 v[170:173], v224 offset:2048
	ds_read_b128 v[178:181], v224 offset:3072
	ds_read_b128 v[202:205], v224 offset:4096
	ds_read_b128 v[206:209], v224 offset:5120
	ds_read_b128 v[226:229], v224 offset:6144
	ds_read_b128 v[230:233], v224 offset:7168
	global_load_lds_dwordx4 v[188:189], off
	v_lshl_add_u64 v[188:189], s[62:63], 0, v[186:187]
	s_add_i32 m0, s17, 0xe000
	s_nop 0
	global_load_lds_dwordx4 v[188:189], off
	s_setprio 1
	s_waitcnt vmcnt(8)
	s_waitcnt lgkmcnt(0)
	s_barrier
	v_mfma_f32_16x16x32_bf16 v[126:129], v[130:133], v[162:165], v[126:129]
	v_mfma_f32_16x16x32_bf16 v[56:59], v[138:141], v[162:165], v[56:59]
	v_mfma_f32_16x16x32_bf16 v[122:125], v[130:133], v[170:173], v[122:125]
	v_mfma_f32_16x16x32_bf16 v[52:55], v[138:141], v[170:173], v[52:55]
	v_mfma_f32_16x16x32_bf16 v[118:121], v[130:133], v[202:205], v[118:121]
	v_mfma_f32_16x16x32_bf16 v[60:63], v[138:141], v[202:205], v[60:63]
	v_mfma_f32_16x16x32_bf16 v[114:117], v[130:133], v[226:229], v[114:117]
	v_mfma_f32_16x16x32_bf16 v[44:47], v[138:141], v[226:229], v[44:47]
	v_mfma_f32_16x16x32_bf16 v[126:129], v[134:137], v[166:169], v[126:129]
	v_mfma_f32_16x16x32_bf16 v[56:59], v[142:145], v[166:169], v[56:59]
	v_mfma_f32_16x16x32_bf16 v[122:125], v[134:137], v[178:181], v[122:125]
	v_mfma_f32_16x16x32_bf16 v[52:55], v[142:145], v[178:181], v[52:55]
	v_mfma_f32_16x16x32_bf16 v[118:121], v[134:137], v[206:209], v[118:121]
	v_mfma_f32_16x16x32_bf16 v[60:63], v[142:145], v[206:209], v[60:63]
	v_mfma_f32_16x16x32_bf16 v[114:117], v[134:137], v[230:233], v[114:117]
	v_mfma_f32_16x16x32_bf16 v[44:47], v[142:145], v[230:233], v[44:47]
	s_setprio 0
	s_setprio 1
	v_mfma_f32_16x16x32_bf16 v[110:113], v[146:149], v[162:165], v[110:113]
	v_mfma_f32_16x16x32_bf16 v[40:43], v[154:157], v[162:165], v[40:43]
	v_mfma_f32_16x16x32_bf16 v[106:109], v[146:149], v[170:173], v[106:109]
	v_mfma_f32_16x16x32_bf16 v[36:39], v[154:157], v[170:173], v[36:39]
	v_mfma_f32_16x16x32_bf16 v[102:105], v[146:149], v[202:205], v[102:105]
	v_mfma_f32_16x16x32_bf16 v[48:51], v[154:157], v[202:205], v[48:51]
	v_mfma_f32_16x16x32_bf16 v[98:101], v[146:149], v[226:229], v[98:101]
	v_mfma_f32_16x16x32_bf16 v[32:35], v[154:157], v[226:229], v[32:35]
	v_mfma_f32_16x16x32_bf16 v[110:113], v[150:153], v[166:169], v[110:113]
	v_mfma_f32_16x16x32_bf16 v[40:43], v[158:161], v[166:169], v[40:43]
	v_mfma_f32_16x16x32_bf16 v[106:109], v[150:153], v[178:181], v[106:109]
	v_mfma_f32_16x16x32_bf16 v[36:39], v[158:161], v[178:181], v[36:39]
	v_mfma_f32_16x16x32_bf16 v[102:105], v[150:153], v[206:209], v[102:105]
	v_mfma_f32_16x16x32_bf16 v[48:51], v[158:161], v[206:209], v[48:51]
	v_mfma_f32_16x16x32_bf16 v[98:101], v[150:153], v[230:233], v[98:101]
	v_mfma_f32_16x16x32_bf16 v[32:35], v[158:161], v[230:233], v[32:35]
	s_setprio 0
	s_barrier
	s_add_i32 s62, s67, s5
	v_lshl_add_u64 v[188:189], vcc, 0, v[96:97]
	s_mov_b32 m0, s62
	ds_read_b128 v[162:165], v224 offset:16384
	ds_read_b128 v[166:169], v224 offset:17408
	ds_read_b128 v[170:173], v224 offset:18432
	ds_read_b128 v[178:181], v224 offset:19456
	ds_read_b128 v[202:205], v224 offset:20480
	ds_read_b128 v[206:209], v224 offset:21504
	ds_read_b128 v[226:229], v224 offset:22528
	ds_read_b128 v[230:233], v224 offset:23552
	global_load_lds_dwordx4 v[188:189], off
	s_add_i32 m0, s62, 0x2000
	s_add_u32 s62, vcc_lo, 0x80000
	v_lshl_add_u64 v[198:199], vcc, 0, v[182:183]
	s_addc_u32 s63, vcc_hi, 0
	s_add_i32 s67, s76, s5
	global_load_lds_dwordx4 v[198:199], off
	v_lshl_add_u64 v[200:201], s[62:63], 0, v[96:97]
	s_mov_b32 m0, s67
	v_lshl_add_u64 v[234:235], s[88:89], 0, v[176:177]
	global_load_lds_dwordx4 v[200:201], off
	v_lshl_add_u64 v[200:201], s[62:63], 0, v[182:183]
	s_add_i32 m0, s67, 0x2000
	s_nop 0
	global_load_lds_dwordx4 v[200:201], off
	v_lshl_add_u64 v[200:201], s[88:89], 0, v[174:175]
	s_mov_b32 m0, s17
	s_nop 0
	global_load_lds_dwordx4 v[200:201], off
	s_mov_b32 m0, s18
	s_nop 0
	global_load_lds_dwordx4 v[234:235], off
	s_setprio 1
	s_waitcnt vmcnt(8)
	s_waitcnt lgkmcnt(0)
	s_barrier
	v_mfma_f32_16x16x32_bf16 v[92:95], v[130:133], v[162:165], v[92:95]
	v_mfma_f32_16x16x32_bf16 v[24:27], v[138:141], v[162:165], v[24:27]
	v_mfma_f32_16x16x32_bf16 v[88:91], v[130:133], v[170:173], v[88:91]
	v_mfma_f32_16x16x32_bf16 v[28:31], v[138:141], v[170:173], v[28:31]
	v_mfma_f32_16x16x32_bf16 v[84:87], v[130:133], v[202:205], v[84:87]
	v_mfma_f32_16x16x32_bf16 v[16:19], v[138:141], v[202:205], v[16:19]
	v_mfma_f32_16x16x32_bf16 v[80:83], v[130:133], v[226:229], v[80:83]
	v_mfma_f32_16x16x32_bf16 v[20:23], v[138:141], v[226:229], v[20:23]
	v_mfma_f32_16x16x32_bf16 v[92:95], v[134:137], v[166:169], v[92:95]
	v_mfma_f32_16x16x32_bf16 v[24:27], v[142:145], v[166:169], v[24:27]
	v_mfma_f32_16x16x32_bf16 v[88:91], v[134:137], v[178:181], v[88:91]
	v_mfma_f32_16x16x32_bf16 v[28:31], v[142:145], v[178:181], v[28:31]
	v_mfma_f32_16x16x32_bf16 v[84:87], v[134:137], v[206:209], v[84:87]
	v_mfma_f32_16x16x32_bf16 v[16:19], v[142:145], v[206:209], v[16:19]
	v_mfma_f32_16x16x32_bf16 v[80:83], v[134:137], v[230:233], v[80:83]
	v_mfma_f32_16x16x32_bf16 v[20:23], v[142:145], v[230:233], v[20:23]
	s_setprio 0
	s_setprio 1
	v_mfma_f32_16x16x32_bf16 v[76:79], v[146:149], v[162:165], v[76:79]
	v_mfma_f32_16x16x32_bf16 v[12:15], v[154:157], v[162:165], v[12:15]
	v_mfma_f32_16x16x32_bf16 v[72:75], v[146:149], v[170:173], v[72:75]
	v_mfma_f32_16x16x32_bf16 v[8:11], v[154:157], v[170:173], v[8:11]
	v_mfma_f32_16x16x32_bf16 v[68:71], v[146:149], v[202:205], v[68:71]
	v_mfma_f32_16x16x32_bf16 v[0:3], v[154:157], v[202:205], v[0:3]
	v_mfma_f32_16x16x32_bf16 v[64:67], v[146:149], v[226:229], v[64:67]
	v_mfma_f32_16x16x32_bf16 v[4:7], v[154:157], v[226:229], v[4:7]
	v_mfma_f32_16x16x32_bf16 v[76:79], v[150:153], v[166:169], v[76:79]
	v_mfma_f32_16x16x32_bf16 v[12:15], v[158:161], v[166:169], v[12:15]
	v_mfma_f32_16x16x32_bf16 v[72:75], v[150:153], v[178:181], v[72:75]
	v_mfma_f32_16x16x32_bf16 v[8:11], v[158:161], v[178:181], v[8:11]
	v_mfma_f32_16x16x32_bf16 v[68:71], v[150:153], v[206:209], v[68:71]
	v_mfma_f32_16x16x32_bf16 v[0:3], v[158:161], v[206:209], v[0:3]
	v_mfma_f32_16x16x32_bf16 v[64:67], v[150:153], v[230:233], v[64:67]
	v_mfma_f32_16x16x32_bf16 v[4:7], v[158:161], v[230:233], v[4:7]
	s_setprio 0
	s_barrier
	s_add_i32 s67, 0, 0x18000
	s_add_i32 s76, 0, 0x1c000
	v_add_u32_e32 v142, s67, v191
	v_add_u32_e32 v158, s76, v191
	ds_read_b128 v[130:133], v142
	ds_read_b128 v[134:137], v142 offset:1024
	ds_read_b128 v[138:141], v142 offset:2048
	ds_read_b128 v[142:145], v142 offset:3072
	ds_read_b128 v[146:149], v158
	ds_read_b128 v[150:153], v158 offset:1024
	ds_read_b128 v[154:157], v158 offset:2048
	ds_read_b128 v[158:161], v158 offset:3072
	s_add_u32 s62, s88, 0x80000
	s_addc_u32 s63, s89, 0
	s_mov_b32 m0, s19
	v_lshl_add_u64 v[236:237], s[62:63], 0, v[174:175]
	ds_read_b128 v[162:165], v224 offset:32768
	ds_read_b128 v[166:169], v224 offset:33792
	ds_read_b128 v[170:173], v224 offset:34816
	ds_read_b128 v[178:181], v224 offset:35840
	ds_read_b128 v[202:205], v224 offset:36864
	ds_read_b128 v[206:209], v224 offset:37888
	ds_read_b128 v[226:229], v224 offset:38912
	ds_read_b128 v[230:233], v224 offset:39936
	global_load_lds_dwordx4 v[236:237], off
	v_lshl_add_u64 v[236:237], s[62:63], 0, v[176:177]
	s_mov_b32 m0, s20
	s_nop 0
	global_load_lds_dwordx4 v[236:237], off
	s_setprio 1
	s_waitcnt vmcnt(8)
	s_waitcnt lgkmcnt(0)
	s_barrier
	v_mfma_f32_16x16x32_bf16 v[126:129], v[130:133], v[162:165], v[126:129]
	v_mfma_f32_16x16x32_bf16 v[56:59], v[138:141], v[162:165], v[56:59]
	v_mfma_f32_16x16x32_bf16 v[122:125], v[130:133], v[170:173], v[122:125]
	v_mfma_f32_16x16x32_bf16 v[52:55], v[138:141], v[170:173], v[52:55]
	v_mfma_f32_16x16x32_bf16 v[118:121], v[130:133], v[202:205], v[118:121]
	v_mfma_f32_16x16x32_bf16 v[60:63], v[138:141], v[202:205], v[60:63]
	v_mfma_f32_16x16x32_bf16 v[114:117], v[130:133], v[226:229], v[114:117]
	v_mfma_f32_16x16x32_bf16 v[44:47], v[138:141], v[226:229], v[44:47]
	v_mfma_f32_16x16x32_bf16 v[126:129], v[134:137], v[166:169], v[126:129]
	v_mfma_f32_16x16x32_bf16 v[56:59], v[142:145], v[166:169], v[56:59]
	v_mfma_f32_16x16x32_bf16 v[122:125], v[134:137], v[178:181], v[122:125]
	v_mfma_f32_16x16x32_bf16 v[52:55], v[142:145], v[178:181], v[52:55]
	v_mfma_f32_16x16x32_bf16 v[118:121], v[134:137], v[206:209], v[118:121]
	v_mfma_f32_16x16x32_bf16 v[60:63], v[142:145], v[206:209], v[60:63]
	v_mfma_f32_16x16x32_bf16 v[114:117], v[134:137], v[230:233], v[114:117]
	v_mfma_f32_16x16x32_bf16 v[44:47], v[142:145], v[230:233], v[44:47]
	s_setprio 0
	s_setprio 1
	v_mfma_f32_16x16x32_bf16 v[110:113], v[146:149], v[162:165], v[110:113]
	v_mfma_f32_16x16x32_bf16 v[40:43], v[154:157], v[162:165], v[40:43]
	v_mfma_f32_16x16x32_bf16 v[106:109], v[146:149], v[170:173], v[106:109]
	v_mfma_f32_16x16x32_bf16 v[36:39], v[154:157], v[170:173], v[36:39]
	v_mfma_f32_16x16x32_bf16 v[102:105], v[146:149], v[202:205], v[102:105]
	v_mfma_f32_16x16x32_bf16 v[48:51], v[154:157], v[202:205], v[48:51]
	v_mfma_f32_16x16x32_bf16 v[98:101], v[146:149], v[226:229], v[98:101]
	v_mfma_f32_16x16x32_bf16 v[32:35], v[154:157], v[226:229], v[32:35]
	v_mfma_f32_16x16x32_bf16 v[110:113], v[150:153], v[166:169], v[110:113]
	v_mfma_f32_16x16x32_bf16 v[40:43], v[158:161], v[166:169], v[40:43]
	v_mfma_f32_16x16x32_bf16 v[106:109], v[150:153], v[178:181], v[106:109]
	v_mfma_f32_16x16x32_bf16 v[36:39], v[158:161], v[178:181], v[36:39]
	v_mfma_f32_16x16x32_bf16 v[102:105], v[150:153], v[206:209], v[102:105]
	v_mfma_f32_16x16x32_bf16 v[48:51], v[158:161], v[206:209], v[48:51]
	v_mfma_f32_16x16x32_bf16 v[98:101], v[150:153], v[230:233], v[98:101]
	v_mfma_f32_16x16x32_bf16 v[32:35], v[158:161], v[230:233], v[32:35]
	s_setprio 0
	s_barrier
	s_add_i32 s62, s67, s5
	v_lshl_add_u64 v[188:189], v[188:189], 0, s[30:31]
	s_mov_b32 m0, s62
	ds_read_b128 v[162:165], v224 offset:49152
	ds_read_b128 v[166:169], v224 offset:50176
	ds_read_b128 v[170:173], v224 offset:51200
	ds_read_b128 v[178:181], v224 offset:52224
	ds_read_b128 v[202:205], v224 offset:53248
	ds_read_b128 v[206:209], v224 offset:54272
	ds_read_b128 v[226:229], v224 offset:55296
	ds_read_b128 v[230:233], v224 offset:56320
	global_load_lds_dwordx4 v[188:189], off
	s_add_i32 m0, s62, 0x2000
	s_add_u32 s62, vcc_lo, 0x80080
	v_lshl_add_u64 v[188:189], v[198:199], 0, s[30:31]
	s_addc_u32 s63, vcc_hi, 0
	s_add_i32 s67, s76, s5
	global_load_lds_dwordx4 v[188:189], off
	v_lshl_add_u64 v[188:189], s[62:63], 0, v[96:97]
	s_mov_b32 m0, s67
	s_nop 0
	global_load_lds_dwordx4 v[188:189], off
	v_lshl_add_u64 v[188:189], s[62:63], 0, v[182:183]
	s_add_i32 m0, s67, 0x2000
	s_nop 0
	global_load_lds_dwordx4 v[188:189], off
	v_lshl_add_u64 v[188:189], v[200:201], 0, s[30:31]
	s_mov_b32 m0, s36
	s_nop 0
	global_load_lds_dwordx4 v[188:189], off
	v_lshl_add_u64 v[188:189], v[234:235], 0, s[30:31]
	s_mov_b32 m0, s37
	s_nop 0
	global_load_lds_dwordx4 v[188:189], off
	s_setprio 1
	s_waitcnt vmcnt(8)
	s_waitcnt lgkmcnt(0)
	s_barrier
	v_mfma_f32_16x16x32_bf16 v[92:95], v[130:133], v[162:165], v[92:95]
	v_mfma_f32_16x16x32_bf16 v[24:27], v[138:141], v[162:165], v[24:27]
	v_mfma_f32_16x16x32_bf16 v[88:91], v[130:133], v[170:173], v[88:91]
	v_mfma_f32_16x16x32_bf16 v[28:31], v[138:141], v[170:173], v[28:31]
	v_mfma_f32_16x16x32_bf16 v[84:87], v[130:133], v[202:205], v[84:87]
	v_mfma_f32_16x16x32_bf16 v[16:19], v[138:141], v[202:205], v[16:19]
	v_mfma_f32_16x16x32_bf16 v[80:83], v[130:133], v[226:229], v[80:83]
	v_mfma_f32_16x16x32_bf16 v[20:23], v[138:141], v[226:229], v[20:23]
	v_mfma_f32_16x16x32_bf16 v[92:95], v[134:137], v[166:169], v[92:95]
	v_mfma_f32_16x16x32_bf16 v[24:27], v[142:145], v[166:169], v[24:27]
	v_mfma_f32_16x16x32_bf16 v[88:91], v[134:137], v[178:181], v[88:91]
	v_mfma_f32_16x16x32_bf16 v[28:31], v[142:145], v[178:181], v[28:31]
	v_mfma_f32_16x16x32_bf16 v[84:87], v[134:137], v[206:209], v[84:87]
	v_mfma_f32_16x16x32_bf16 v[16:19], v[142:145], v[206:209], v[16:19]
	v_mfma_f32_16x16x32_bf16 v[80:83], v[134:137], v[230:233], v[80:83]
	v_mfma_f32_16x16x32_bf16 v[20:23], v[142:145], v[230:233], v[20:23]
	s_setprio 0
	s_setprio 1
	v_mfma_f32_16x16x32_bf16 v[76:79], v[146:149], v[162:165], v[76:79]
	v_mfma_f32_16x16x32_bf16 v[12:15], v[154:157], v[162:165], v[12:15]
	v_mfma_f32_16x16x32_bf16 v[72:75], v[146:149], v[170:173], v[72:75]
	v_mfma_f32_16x16x32_bf16 v[8:11], v[154:157], v[170:173], v[8:11]
	v_mfma_f32_16x16x32_bf16 v[68:71], v[146:149], v[202:205], v[68:71]
	v_mfma_f32_16x16x32_bf16 v[0:3], v[154:157], v[202:205], v[0:3]
	v_mfma_f32_16x16x32_bf16 v[64:67], v[146:149], v[226:229], v[64:67]
	v_mfma_f32_16x16x32_bf16 v[4:7], v[154:157], v[226:229], v[4:7]
	v_mfma_f32_16x16x32_bf16 v[76:79], v[150:153], v[166:169], v[76:79]
	v_mfma_f32_16x16x32_bf16 v[12:15], v[158:161], v[166:169], v[12:15]
	v_mfma_f32_16x16x32_bf16 v[72:75], v[150:153], v[178:181], v[72:75]
	v_mfma_f32_16x16x32_bf16 v[8:11], v[158:161], v[178:181], v[8:11]
	v_mfma_f32_16x16x32_bf16 v[68:71], v[150:153], v[206:209], v[68:71]
	v_mfma_f32_16x16x32_bf16 v[0:3], v[158:161], v[206:209], v[0:3]
	v_mfma_f32_16x16x32_bf16 v[64:67], v[150:153], v[230:233], v[64:67]
	v_mfma_f32_16x16x32_bf16 v[4:7], v[158:161], v[230:233], v[4:7]
	s_setprio 0
	s_barrier
	s_add_i32 s6, s6, 2
	s_add_u32 s2, s2, 0x100
	s_addc_u32 s3, s3, 0
	s_cmp_gt_u32 s6, 29
	s_mov_b64 s[62:63], s[34:35]
	s_cbranch_scc0 .LBB0_1158
	s_nop 0
	s_nop 0
	s_nop 0
	s_nop 0
	s_and_b64 vcc, exec, s[24:25]
	s_cbranch_vccz .LBB0_1161
	s_barrier

.LBB0_1333:
	s_add_u32 s38, s42, 0x100
	s_addc_u32 s39, s43, 0
	s_add_i32 s13, 0, 0x10000
	s_cmp_eq_u32 s6, 4
	s_cselect_b32 s47, s25, s39
	s_cselect_b32 s46, s24, s38
	s_cselect_b32 s45, s35, s3
	s_cselect_b32 s44, s34, s2
	s_add_i32 s23, 0, 0x14000
	v_add_u32_e32 v152, s13, v136
	v_add_u32_e32 v168, s23, v136
	ds_read_b128 v[140:143], v152
	ds_read_b128 v[144:147], v152 offset:1024
	ds_read_b128 v[148:151], v152 offset:2048
	ds_read_b128 v[152:155], v152 offset:3072
	ds_read_b128 v[156:159], v168
	ds_read_b128 v[160:163], v168 offset:1024
	ds_read_b128 v[164:167], v168 offset:2048
	ds_read_b128 v[168:171], v168 offset:3072
	v_lshl_add_u64 v[198:199], s[42:43], 0, v[132:133]
	s_add_i32 m0, s5, 0xc000
	ds_read_b128 v[172:175], v139
	ds_read_b128 v[176:179], v139 offset:1024
	ds_read_b128 v[180:183], v139 offset:2048
	ds_read_b128 v[184:187], v139 offset:3072
	ds_read_b128 v[188:191], v139 offset:4096
	ds_read_b128 v[192:195], v139 offset:5120
	ds_read_b128 v[202:205], v139 offset:6144
	ds_read_b128 v[206:209], v139 offset:7168
	global_load_lds_dwordx4 v[198:199], off
	v_lshl_add_u64 v[198:199], s[42:43], 0, v[134:135]
	s_add_i32 m0, s5, 0xe000
	s_nop 0
	global_load_lds_dwordx4 v[198:199], off
	s_setprio 1
	s_waitcnt vmcnt(8)
	s_waitcnt lgkmcnt(0)
	s_barrier
	v_mfma_f32_16x16x32_bf16 v[126:129], v[140:143], v[172:175], v[126:129]
	v_mfma_f32_16x16x32_bf16 v[122:125], v[148:151], v[172:175], v[122:125]
	v_mfma_f32_16x16x32_bf16 v[118:121], v[140:143], v[180:183], v[118:121]
	v_mfma_f32_16x16x32_bf16 v[114:117], v[148:151], v[180:183], v[114:117]
	v_mfma_f32_16x16x32_bf16 v[106:109], v[140:143], v[188:191], v[106:109]
	v_mfma_f32_16x16x32_bf16 v[98:101], v[148:151], v[188:191], v[98:101]
	v_mfma_f32_16x16x32_bf16 v[88:91], v[140:143], v[202:205], v[88:91]
	v_mfma_f32_16x16x32_bf16 v[80:83], v[148:151], v[202:205], v[80:83]
	v_mfma_f32_16x16x32_bf16 v[126:129], v[144:147], v[176:179], v[126:129]
	v_mfma_f32_16x16x32_bf16 v[122:125], v[152:155], v[176:179], v[122:125]
	v_mfma_f32_16x16x32_bf16 v[118:121], v[144:147], v[184:187], v[118:121]
	v_mfma_f32_16x16x32_bf16 v[114:117], v[152:155], v[184:187], v[114:117]
	v_mfma_f32_16x16x32_bf16 v[106:109], v[144:147], v[192:195], v[106:109]
	v_mfma_f32_16x16x32_bf16 v[98:101], v[152:155], v[192:195], v[98:101]
	v_mfma_f32_16x16x32_bf16 v[88:91], v[144:147], v[206:209], v[88:91]
	v_mfma_f32_16x16x32_bf16 v[80:83], v[152:155], v[206:209], v[80:83]
	s_setprio 0
	s_setprio 1
	v_mfma_f32_16x16x32_bf16 v[110:113], v[156:159], v[172:175], v[110:113]
	v_mfma_f32_16x16x32_bf16 v[102:105], v[164:167], v[172:175], v[102:105]
	v_mfma_f32_16x16x32_bf16 v[92:95], v[156:159], v[180:183], v[92:95]
	v_mfma_f32_16x16x32_bf16 v[84:87], v[164:167], v[180:183], v[84:87]
	v_mfma_f32_16x16x32_bf16 v[76:79], v[156:159], v[188:191], v[76:79]
	v_mfma_f32_16x16x32_bf16 v[72:75], v[164:167], v[188:191], v[72:75]
	v_mfma_f32_16x16x32_bf16 v[68:71], v[156:159], v[202:205], v[68:71]
	v_mfma_f32_16x16x32_bf16 v[64:67], v[164:167], v[202:205], v[64:67]
	v_mfma_f32_16x16x32_bf16 v[110:113], v[160:163], v[176:179], v[110:113]
	v_mfma_f32_16x16x32_bf16 v[102:105], v[168:171], v[176:179], v[102:105]
	v_mfma_f32_16x16x32_bf16 v[92:95], v[160:163], v[184:187], v[92:95]
	v_mfma_f32_16x16x32_bf16 v[84:87], v[168:171], v[184:187], v[84:87]
	v_mfma_f32_16x16x32_bf16 v[76:79], v[160:163], v[192:195], v[76:79]
	v_mfma_f32_16x16x32_bf16 v[72:75], v[168:171], v[192:195], v[72:75]
	v_mfma_f32_16x16x32_bf16 v[68:71], v[160:163], v[206:209], v[68:71]
	v_mfma_f32_16x16x32_bf16 v[64:67], v[168:171], v[206:209], v[64:67]
	s_setprio 0
	s_barrier
	s_add_i32 s13, s13, s4
	v_lshl_add_u64 v[198:199], s[44:45], 0, v[96:97]
	s_mov_b32 m0, s13
	ds_read_b128 v[172:175], v139 offset:16384
	ds_read_b128 v[176:179], v139 offset:17408
	ds_read_b128 v[180:183], v139 offset:18432
	ds_read_b128 v[184:187], v139 offset:19456
	ds_read_b128 v[188:191], v139 offset:20480
	ds_read_b128 v[192:195], v139 offset:21504
	ds_read_b128 v[202:205], v139 offset:22528
	ds_read_b128 v[206:209], v139 offset:23552
	global_load_lds_dwordx4 v[198:199], off
	s_add_i32 m0, s13, 0x2000
	s_add_u32 s42, s44, 0x160000
	v_lshl_add_u64 v[200:201], s[44:45], 0, v[130:131]
	s_addc_u32 s43, s45, 0
	s_add_i32 s13, s23, s4
	global_load_lds_dwordx4 v[200:201], off
	v_lshl_add_u64 v[214:215], s[42:43], 0, v[96:97]
	s_mov_b32 m0, s13
	v_lshl_add_u64 v[216:217], s[46:47], 0, v[130:131]
	global_load_lds_dwordx4 v[214:215], off
	v_lshl_add_u64 v[214:215], s[42:43], 0, v[130:131]
	s_add_i32 m0, s13, 0x2000
	s_nop 0
	global_load_lds_dwordx4 v[214:215], off
	v_lshl_add_u64 v[214:215], s[46:47], 0, v[96:97]
	s_mov_b32 m0, s5
	s_nop 0
	global_load_lds_dwordx4 v[214:215], off
	s_mov_b32 m0, s17
	s_nop 0
	global_load_lds_dwordx4 v[216:217], off
	s_setprio 1
	s_waitcnt vmcnt(8)
	s_waitcnt lgkmcnt(0)
	s_barrier
	v_mfma_f32_16x16x32_bf16 v[60:63], v[140:143], v[172:175], v[60:63]
	v_mfma_f32_16x16x32_bf16 v[56:59], v[148:151], v[172:175], v[56:59]
	v_mfma_f32_16x16x32_bf16 v[52:55], v[140:143], v[180:183], v[52:55]
	v_mfma_f32_16x16x32_bf16 v[48:51], v[148:151], v[180:183], v[48:51]
	v_mfma_f32_16x16x32_bf16 v[36:39], v[140:143], v[188:191], v[36:39]
	v_mfma_f32_16x16x32_bf16 v[32:35], v[148:151], v[188:191], v[32:35]
	v_mfma_f32_16x16x32_bf16 v[20:23], v[140:143], v[202:205], v[20:23]
	v_mfma_f32_16x16x32_bf16 v[16:19], v[148:151], v[202:205], v[16:19]
	v_mfma_f32_16x16x32_bf16 v[60:63], v[144:147], v[176:179], v[60:63]
	v_mfma_f32_16x16x32_bf16 v[56:59], v[152:155], v[176:179], v[56:59]
	v_mfma_f32_16x16x32_bf16 v[52:55], v[144:147], v[184:187], v[52:55]
	v_mfma_f32_16x16x32_bf16 v[48:51], v[152:155], v[184:187], v[48:51]
	v_mfma_f32_16x16x32_bf16 v[36:39], v[144:147], v[192:195], v[36:39]
	v_mfma_f32_16x16x32_bf16 v[32:35], v[152:155], v[192:195], v[32:35]
	v_mfma_f32_16x16x32_bf16 v[20:23], v[144:147], v[206:209], v[20:23]
	v_mfma_f32_16x16x32_bf16 v[16:19], v[152:155], v[206:209], v[16:19]
	s_setprio 0
	s_setprio 1
	v_mfma_f32_16x16x32_bf16 v[44:47], v[156:159], v[172:175], v[44:47]
	v_mfma_f32_16x16x32_bf16 v[40:43], v[164:167], v[172:175], v[40:43]
	v_mfma_f32_16x16x32_bf16 v[28:31], v[156:159], v[180:183], v[28:31]
	v_mfma_f32_16x16x32_bf16 v[24:27], v[164:167], v[180:183], v[24:27]
	v_mfma_f32_16x16x32_bf16 v[12:15], v[156:159], v[188:191], v[12:15]
	v_mfma_f32_16x16x32_bf16 v[8:11], v[164:167], v[188:191], v[8:11]
	v_mfma_f32_16x16x32_bf16 v[4:7], v[156:159], v[202:205], v[4:7]
	v_mfma_f32_16x16x32_bf16 v[0:3], v[164:167], v[202:205], v[0:3]
	v_mfma_f32_16x16x32_bf16 v[44:47], v[160:163], v[176:179], v[44:47]
	v_mfma_f32_16x16x32_bf16 v[40:43], v[168:171], v[176:179], v[40:43]
	v_mfma_f32_16x16x32_bf16 v[28:31], v[160:163], v[184:187], v[28:31]
	v_mfma_f32_16x16x32_bf16 v[24:27], v[168:171], v[184:187], v[24:27]
	v_mfma_f32_16x16x32_bf16 v[12:15], v[160:163], v[192:195], v[12:15]
	v_mfma_f32_16x16x32_bf16 v[8:11], v[168:171], v[192:195], v[8:11]
	v_mfma_f32_16x16x32_bf16 v[4:7], v[160:163], v[206:209], v[4:7]
	v_mfma_f32_16x16x32_bf16 v[0:3], v[168:171], v[206:209], v[0:3]
	s_setprio 0
	s_barrier
	s_add_i32 s13, 0, 0x18000
	s_add_i32 s23, 0, 0x1c000
	v_add_u32_e32 v152, s13, v136
	v_add_u32_e32 v168, s23, v136
	ds_read_b128 v[140:143], v152
	ds_read_b128 v[144:147], v152 offset:1024
	ds_read_b128 v[148:151], v152 offset:2048
	ds_read_b128 v[152:155], v152 offset:3072
	ds_read_b128 v[156:159], v168
	ds_read_b128 v[160:163], v168 offset:1024
	ds_read_b128 v[164:167], v168 offset:2048
	ds_read_b128 v[168:171], v168 offset:3072
	s_add_u32 s42, s46, 0x160000
	s_addc_u32 s43, s47, 0
	s_mov_b32 m0, s18
	v_lshl_add_u64 v[218:219], s[42:43], 0, v[96:97]
	ds_read_b128 v[172:175], v139 offset:32768
	ds_read_b128 v[176:179], v139 offset:33792
	ds_read_b128 v[180:183], v139 offset:34816
	ds_read_b128 v[184:187], v139 offset:35840
	ds_read_b128 v[188:191], v139 offset:36864
	ds_read_b128 v[192:195], v139 offset:37888
	ds_read_b128 v[202:205], v139 offset:38912
	ds_read_b128 v[206:209], v139 offset:39936
	global_load_lds_dwordx4 v[218:219], off
	v_lshl_add_u64 v[218:219], s[42:43], 0, v[130:131]
	s_mov_b32 m0, s19
	s_nop 0
	global_load_lds_dwordx4 v[218:219], off
	s_setprio 1
	s_waitcnt vmcnt(8)
	s_waitcnt lgkmcnt(0)
	s_barrier
	v_mfma_f32_16x16x32_bf16 v[126:129], v[140:143], v[172:175], v[126:129]
	v_mfma_f32_16x16x32_bf16 v[122:125], v[148:151], v[172:175], v[122:125]
	v_mfma_f32_16x16x32_bf16 v[118:121], v[140:143], v[180:183], v[118:121]
	v_mfma_f32_16x16x32_bf16 v[114:117], v[148:151], v[180:183], v[114:117]
	v_mfma_f32_16x16x32_bf16 v[106:109], v[140:143], v[188:191], v[106:109]
	v_mfma_f32_16x16x32_bf16 v[98:101], v[148:151], v[188:191], v[98:101]
	v_mfma_f32_16x16x32_bf16 v[88:91], v[140:143], v[202:205], v[88:91]
	v_mfma_f32_16x16x32_bf16 v[80:83], v[148:151], v[202:205], v[80:83]
	v_mfma_f32_16x16x32_bf16 v[126:129], v[144:147], v[176:179], v[126:129]
	v_mfma_f32_16x16x32_bf16 v[122:125], v[152:155], v[176:179], v[122:125]
	v_mfma_f32_16x16x32_bf16 v[118:121], v[144:147], v[184:187], v[118:121]
	v_mfma_f32_16x16x32_bf16 v[114:117], v[152:155], v[184:187], v[114:117]
	v_mfma_f32_16x16x32_bf16 v[106:109], v[144:147], v[192:195], v[106:109]
	v_mfma_f32_16x16x32_bf16 v[98:101], v[152:155], v[192:195], v[98:101]
	v_mfma_f32_16x16x32_bf16 v[88:91], v[144:147], v[206:209], v[88:91]
	v_mfma_f32_16x16x32_bf16 v[80:83], v[152:155], v[206:209], v[80:83]
	s_setprio 0
	s_setprio 1
	v_mfma_f32_16x16x32_bf16 v[110:113], v[156:159], v[172:175], v[110:113]
	v_mfma_f32_16x16x32_bf16 v[102:105], v[164:167], v[172:175], v[102:105]
	v_mfma_f32_16x16x32_bf16 v[92:95], v[156:159], v[180:183], v[92:95]
	v_mfma_f32_16x16x32_bf16 v[84:87], v[164:167], v[180:183], v[84:87]
	v_mfma_f32_16x16x32_bf16 v[76:79], v[156:159], v[188:191], v[76:79]
	v_mfma_f32_16x16x32_bf16 v[72:75], v[164:167], v[188:191], v[72:75]
	v_mfma_f32_16x16x32_bf16 v[68:71], v[156:159], v[202:205], v[68:71]
	v_mfma_f32_16x16x32_bf16 v[64:67], v[164:167], v[202:205], v[64:67]
	v_mfma_f32_16x16x32_bf16 v[110:113], v[160:163], v[176:179], v[110:113]
	v_mfma_f32_16x16x32_bf16 v[102:105], v[168:171], v[176:179], v[102:105]
	v_mfma_f32_16x16x32_bf16 v[92:95], v[160:163], v[184:187], v[92:95]
	v_mfma_f32_16x16x32_bf16 v[84:87], v[168:171], v[184:187], v[84:87]
	v_mfma_f32_16x16x32_bf16 v[76:79], v[160:163], v[192:195], v[76:79]
	v_mfma_f32_16x16x32_bf16 v[72:75], v[168:171], v[192:195], v[72:75]
	v_mfma_f32_16x16x32_bf16 v[68:71], v[160:163], v[206:209], v[68:71]
	v_mfma_f32_16x16x32_bf16 v[64:67], v[168:171], v[206:209], v[64:67]
	s_setprio 0
	s_barrier
	s_add_i32 s13, s13, s4
	v_lshl_add_u64 v[198:199], v[198:199], 0, s[30:31]
	s_mov_b32 m0, s13
	ds_read_b128 v[172:175], v139 offset:49152
	ds_read_b128 v[176:179], v139 offset:50176
	ds_read_b128 v[180:183], v139 offset:51200
	ds_read_b128 v[184:187], v139 offset:52224
	ds_read_b128 v[188:191], v139 offset:53248
	ds_read_b128 v[192:195], v139 offset:54272
	ds_read_b128 v[202:205], v139 offset:55296
	ds_read_b128 v[206:209], v139 offset:56320
	global_load_lds_dwordx4 v[198:199], off
	s_add_i32 m0, s13, 0x2000
	s_add_u32 s42, s44, 0x160080
	v_lshl_add_u64 v[198:199], v[200:201], 0, s[30:31]
	s_addc_u32 s43, s45, 0
	s_add_i32 s13, s23, s4
	global_load_lds_dwordx4 v[198:199], off
	v_lshl_add_u64 v[198:199], s[42:43], 0, v[96:97]
	s_mov_b32 m0, s13
	s_nop 0
	global_load_lds_dwordx4 v[198:199], off
	v_lshl_add_u64 v[198:199], s[42:43], 0, v[130:131]
	s_add_i32 m0, s13, 0x2000
	s_nop 0
	global_load_lds_dwordx4 v[198:199], off
	v_lshl_add_u64 v[198:199], v[214:215], 0, s[30:31]
	s_mov_b32 m0, s37
	s_nop 0
	global_load_lds_dwordx4 v[198:199], off
	v_lshl_add_u64 v[198:199], v[216:217], 0, s[30:31]
	s_mov_b32 m0, s40
	s_nop 0
	global_load_lds_dwordx4 v[198:199], off
	s_setprio 1
	s_waitcnt vmcnt(8)
	s_waitcnt lgkmcnt(0)
	s_barrier
	v_mfma_f32_16x16x32_bf16 v[60:63], v[140:143], v[172:175], v[60:63]
	v_mfma_f32_16x16x32_bf16 v[56:59], v[148:151], v[172:175], v[56:59]
	v_mfma_f32_16x16x32_bf16 v[52:55], v[140:143], v[180:183], v[52:55]
	v_mfma_f32_16x16x32_bf16 v[48:51], v[148:151], v[180:183], v[48:51]
	v_mfma_f32_16x16x32_bf16 v[36:39], v[140:143], v[188:191], v[36:39]
	v_mfma_f32_16x16x32_bf16 v[32:35], v[148:151], v[188:191], v[32:35]
	v_mfma_f32_16x16x32_bf16 v[20:23], v[140:143], v[202:205], v[20:23]
	v_mfma_f32_16x16x32_bf16 v[16:19], v[148:151], v[202:205], v[16:19]
	v_mfma_f32_16x16x32_bf16 v[60:63], v[144:147], v[176:179], v[60:63]
	v_mfma_f32_16x16x32_bf16 v[56:59], v[152:155], v[176:179], v[56:59]
	v_mfma_f32_16x16x32_bf16 v[52:55], v[144:147], v[184:187], v[52:55]
	v_mfma_f32_16x16x32_bf16 v[48:51], v[152:155], v[184:187], v[48:51]
	v_mfma_f32_16x16x32_bf16 v[36:39], v[144:147], v[192:195], v[36:39]
	v_mfma_f32_16x16x32_bf16 v[32:35], v[152:155], v[192:195], v[32:35]
	v_mfma_f32_16x16x32_bf16 v[20:23], v[144:147], v[206:209], v[20:23]
	v_mfma_f32_16x16x32_bf16 v[16:19], v[152:155], v[206:209], v[16:19]
	s_setprio 0
	s_setprio 1
	v_mfma_f32_16x16x32_bf16 v[44:47], v[156:159], v[172:175], v[44:47]
	v_mfma_f32_16x16x32_bf16 v[40:43], v[164:167], v[172:175], v[40:43]
	v_mfma_f32_16x16x32_bf16 v[28:31], v[156:159], v[180:183], v[28:31]
	v_mfma_f32_16x16x32_bf16 v[24:27], v[164:167], v[180:183], v[24:27]
	v_mfma_f32_16x16x32_bf16 v[12:15], v[156:159], v[188:191], v[12:15]
	v_mfma_f32_16x16x32_bf16 v[8:11], v[164:167], v[188:191], v[8:11]
	v_mfma_f32_16x16x32_bf16 v[4:7], v[156:159], v[202:205], v[4:7]
	v_mfma_f32_16x16x32_bf16 v[0:3], v[164:167], v[202:205], v[0:3]
	v_mfma_f32_16x16x32_bf16 v[44:47], v[160:163], v[176:179], v[44:47]
	v_mfma_f32_16x16x32_bf16 v[40:43], v[168:171], v[176:179], v[40:43]
	v_mfma_f32_16x16x32_bf16 v[28:31], v[160:163], v[184:187], v[28:31]
	v_mfma_f32_16x16x32_bf16 v[24:27], v[168:171], v[184:187], v[24:27]
	v_mfma_f32_16x16x32_bf16 v[12:15], v[160:163], v[192:195], v[12:15]
	v_mfma_f32_16x16x32_bf16 v[8:11], v[168:171], v[192:195], v[8:11]
	v_mfma_f32_16x16x32_bf16 v[4:7], v[160:163], v[206:209], v[4:7]
	v_mfma_f32_16x16x32_bf16 v[0:3], v[168:171], v[206:209], v[0:3]
	s_setprio 0
	s_barrier
	s_add_i32 s6, s6, 2
	s_add_u32 s2, s2, 0x100
	s_addc_u32 s3, s3, 0
	s_cmp_gt_u32 s6, 5
	s_mov_b64 s[42:43], s[38:39]
	s_cbranch_scc0 .LBB0_1333
	s_nop 0
	s_nop 0
	s_nop 0
	s_nop 0
	s_and_b64 vcc, exec, s[14:15]
	s_cbranch_vccz .LBB0_1336
	s_barrier

.LBB0_1357:
	s_add_u32 s3, s14, s34
	s_addc_u32 s6, s15, s35
	s_add_u32 s3, s3, 0x100
	s_addc_u32 s6, s6, 0
	s_add_u32 s42, s57, s34
	s_addc_u32 s43, s58, s35
	s_add_i32 s59, 0, 0x10000
	s_cmpk_eq_i32 s34, 0x2b00
	s_cselect_b32 s45, s23, s6
	s_cselect_b32 s44, s22, s3
	v_add_u32_e32 v146, s59, v144
	s_cselect_b32 s43, s25, s43
	s_cselect_b32 s42, s24, s42
	s_add_i32 s3, 0, 0x14000
	ds_read_b128 v[154:157], v146
	ds_read_b128 v[158:161], v146 offset:1024
	ds_read_b128 v[162:165], v146 offset:2048
	ds_read_b128 v[166:169], v146 offset:3072
	v_add_u32_e32 v146, s3, v144
	ds_read_b128 v[174:177], v146
	ds_read_b128 v[178:181], v146 offset:1024
	ds_read_b128 v[182:185], v146 offset:2048
	ds_read_b128 v[186:189], v146 offset:3072
	v_lshl_add_u64 v[146:147], v[140:141], 0, s[34:35]
	s_add_i32 m0, s17, 0xc000
	ds_read_b128 v[190:193], v145
	ds_read_b128 v[202:205], v145 offset:1024
	ds_read_b128 v[206:209], v145 offset:2048
	ds_read_b128 v[214:217], v145 offset:3072
	ds_read_b128 v[218:221], v145 offset:4096
	ds_read_b128 v[222:225], v145 offset:5120
	ds_read_b128 v[226:229], v145 offset:6144
	ds_read_b128 v[230:233], v145 offset:7168
	global_load_lds_dwordx4 v[146:147], off
	v_lshl_add_u64 v[146:147], v[142:143], 0, s[34:35]
	s_add_i32 m0, s17, 0xe000
	s_nop 0
	global_load_lds_dwordx4 v[146:147], off
	s_setprio 1
	s_waitcnt vmcnt(8)
	s_waitcnt lgkmcnt(0)
	s_barrier
	v_mfma_f32_16x16x32_bf16 v[110:113], v[154:157], v[190:193], v[110:113]
	v_mfma_f32_16x16x32_bf16 v[106:109], v[162:165], v[190:193], v[106:109]
	v_mfma_f32_16x16x32_bf16 v[118:121], v[154:157], v[206:209], v[118:121]
	v_mfma_f32_16x16x32_bf16 v[114:117], v[162:165], v[206:209], v[114:117]
	v_mfma_f32_16x16x32_bf16 v[126:129], v[154:157], v[218:221], v[126:129]
	v_mfma_f32_16x16x32_bf16 v[122:125], v[162:165], v[218:221], v[122:125]
	v_mfma_f32_16x16x32_bf16 v[92:95], v[154:157], v[226:229], v[92:95]
	v_mfma_f32_16x16x32_bf16 v[88:91], v[162:165], v[226:229], v[88:91]
	v_mfma_f32_16x16x32_bf16 v[110:113], v[158:161], v[202:205], v[110:113]
	v_mfma_f32_16x16x32_bf16 v[106:109], v[166:169], v[202:205], v[106:109]
	v_mfma_f32_16x16x32_bf16 v[118:121], v[158:161], v[214:217], v[118:121]
	v_mfma_f32_16x16x32_bf16 v[114:117], v[166:169], v[214:217], v[114:117]
	v_mfma_f32_16x16x32_bf16 v[126:129], v[158:161], v[222:225], v[126:129]
	v_mfma_f32_16x16x32_bf16 v[122:125], v[166:169], v[222:225], v[122:125]
	v_mfma_f32_16x16x32_bf16 v[92:95], v[158:161], v[230:233], v[92:95]
	v_mfma_f32_16x16x32_bf16 v[88:91], v[166:169], v[230:233], v[88:91]
	s_setprio 0
	s_setprio 1
	v_mfma_f32_16x16x32_bf16 v[4:7], v[174:177], v[190:193], v[4:7]
	v_mfma_f32_16x16x32_bf16 v[0:3], v[182:185], v[190:193], v[0:3]
	v_mfma_f32_16x16x32_bf16 v[12:15], v[174:177], v[206:209], v[12:15]
	v_mfma_f32_16x16x32_bf16 v[8:11], v[182:185], v[206:209], v[8:11]
	v_mfma_f32_16x16x32_bf16 v[24:27], v[174:177], v[218:221], v[24:27]
	v_mfma_f32_16x16x32_bf16 v[20:23], v[182:185], v[218:221], v[20:23]
	v_mfma_f32_16x16x32_bf16 v[40:43], v[174:177], v[226:229], v[40:43]
	v_mfma_f32_16x16x32_bf16 v[36:39], v[182:185], v[226:229], v[36:39]
	v_mfma_f32_16x16x32_bf16 v[4:7], v[178:181], v[202:205], v[4:7]
	v_mfma_f32_16x16x32_bf16 v[0:3], v[186:189], v[202:205], v[0:3]
	v_mfma_f32_16x16x32_bf16 v[12:15], v[178:181], v[214:217], v[12:15]
	v_mfma_f32_16x16x32_bf16 v[8:11], v[186:189], v[214:217], v[8:11]
	v_mfma_f32_16x16x32_bf16 v[24:27], v[178:181], v[222:225], v[24:27]
	v_mfma_f32_16x16x32_bf16 v[20:23], v[186:189], v[222:225], v[20:23]
	v_mfma_f32_16x16x32_bf16 v[40:43], v[178:181], v[230:233], v[40:43]
	v_mfma_f32_16x16x32_bf16 v[36:39], v[186:189], v[230:233], v[36:39]
	s_setprio 0
	s_barrier
	s_add_i32 s6, s59, s5
	v_lshl_add_u64 v[146:147], s[42:43], 0, v[96:97]
	s_mov_b32 m0, s6
	ds_read_b128 v[190:193], v145 offset:16384
	ds_read_b128 v[202:205], v145 offset:17408
	ds_read_b128 v[206:209], v145 offset:18432
	ds_read_b128 v[214:217], v145 offset:19456
	ds_read_b128 v[218:221], v145 offset:20480
	ds_read_b128 v[222:225], v145 offset:21504
	ds_read_b128 v[226:229], v145 offset:22528
	ds_read_b128 v[230:233], v145 offset:23552
	global_load_lds_dwordx4 v[146:147], off
	s_add_i32 m0, s6, 0x2000
	s_add_u32 s60, s42, 0x160000
	v_lshl_add_u64 v[150:151], s[42:43], 0, v[130:131]
	s_addc_u32 s61, s43, 0
	s_add_i32 s3, s3, s5
	global_load_lds_dwordx4 v[150:151], off
	v_lshl_add_u64 v[170:171], s[60:61], 0, v[96:97]
	s_mov_b32 m0, s3
	v_lshl_add_u64 v[194:195], s[44:45], 0, v[132:133]
	global_load_lds_dwordx4 v[170:171], off
	v_lshl_add_u64 v[170:171], s[60:61], 0, v[130:131]
	s_add_i32 m0, s3, 0x2000
	s_nop 0
	global_load_lds_dwordx4 v[170:171], off
	v_lshl_add_u64 v[170:171], s[44:45], 0, v[134:135]
	s_mov_b32 m0, s17
	s_nop 0
	global_load_lds_dwordx4 v[170:171], off
	s_mov_b32 m0, s18
	s_nop 0
	global_load_lds_dwordx4 v[194:195], off
	s_setprio 1
	s_waitcnt vmcnt(8)
	s_waitcnt lgkmcnt(0)
	s_barrier
	v_mfma_f32_16x16x32_bf16 v[102:105], v[154:157], v[190:193], v[102:105]
	v_mfma_f32_16x16x32_bf16 v[98:101], v[162:165], v[190:193], v[98:101]
	v_mfma_f32_16x16x32_bf16 v[84:87], v[154:157], v[206:209], v[84:87]
	v_mfma_f32_16x16x32_bf16 v[80:83], v[162:165], v[206:209], v[80:83]
	v_mfma_f32_16x16x32_bf16 v[68:71], v[154:157], v[218:221], v[68:71]
	v_mfma_f32_16x16x32_bf16 v[64:67], v[162:165], v[218:221], v[64:67]
	v_mfma_f32_16x16x32_bf16 v[44:47], v[154:157], v[226:229], v[44:47]
	v_mfma_f32_16x16x32_bf16 v[32:35], v[162:165], v[226:229], v[32:35]
	v_mfma_f32_16x16x32_bf16 v[102:105], v[158:161], v[202:205], v[102:105]
	v_mfma_f32_16x16x32_bf16 v[98:101], v[166:169], v[202:205], v[98:101]
	v_mfma_f32_16x16x32_bf16 v[84:87], v[158:161], v[214:217], v[84:87]
	v_mfma_f32_16x16x32_bf16 v[80:83], v[166:169], v[214:217], v[80:83]
	v_mfma_f32_16x16x32_bf16 v[68:71], v[158:161], v[222:225], v[68:71]
	v_mfma_f32_16x16x32_bf16 v[64:67], v[166:169], v[222:225], v[64:67]
	v_mfma_f32_16x16x32_bf16 v[44:47], v[158:161], v[230:233], v[44:47]
	v_mfma_f32_16x16x32_bf16 v[32:35], v[166:169], v[230:233], v[32:35]
	s_setprio 0
	s_setprio 1
	v_mfma_f32_16x16x32_bf16 v[60:63], v[174:177], v[190:193], v[60:63]
	v_mfma_f32_16x16x32_bf16 v[56:59], v[182:185], v[190:193], v[56:59]
	v_mfma_f32_16x16x32_bf16 v[76:79], v[174:177], v[206:209], v[76:79]
	v_mfma_f32_16x16x32_bf16 v[72:75], v[182:185], v[206:209], v[72:75]
	v_mfma_f32_16x16x32_bf16 v[52:55], v[174:177], v[218:221], v[52:55]
	v_mfma_f32_16x16x32_bf16 v[48:51], v[182:185], v[218:221], v[48:51]
	v_mfma_f32_16x16x32_bf16 v[28:31], v[174:177], v[226:229], v[28:31]
	v_mfma_f32_16x16x32_bf16 v[16:19], v[182:185], v[226:229], v[16:19]
	v_mfma_f32_16x16x32_bf16 v[60:63], v[178:181], v[202:205], v[60:63]
	v_mfma_f32_16x16x32_bf16 v[56:59], v[186:189], v[202:205], v[56:59]
	v_mfma_f32_16x16x32_bf16 v[76:79], v[178:181], v[214:217], v[76:79]
	v_mfma_f32_16x16x32_bf16 v[72:75], v[186:189], v[214:217], v[72:75]
	v_mfma_f32_16x16x32_bf16 v[52:55], v[178:181], v[222:225], v[52:55]
	v_mfma_f32_16x16x32_bf16 v[48:51], v[186:189], v[222:225], v[48:51]
	v_mfma_f32_16x16x32_bf16 v[28:31], v[178:181], v[230:233], v[28:31]
	v_mfma_f32_16x16x32_bf16 v[16:19], v[186:189], v[230:233], v[16:19]
	s_setprio 0
	s_barrier
	s_add_i32 s3, 0, 0x18000
	v_add_u32_e32 v149, s3, v144
	s_add_i32 s6, 0, 0x1c000
	ds_read_b128 v[154:157], v149
	ds_read_b128 v[158:161], v149 offset:1024
	ds_read_b128 v[162:165], v149 offset:2048
	ds_read_b128 v[166:169], v149 offset:3072
	v_add_u32_e32 v149, s6, v144
	ds_read_b128 v[174:177], v149
	ds_read_b128 v[178:181], v149 offset:1024
	ds_read_b128 v[182:185], v149 offset:2048
	ds_read_b128 v[186:189], v149 offset:3072
	s_add_u32 s44, s44, 0x160000
	s_addc_u32 s45, s45, 0
	s_mov_b32 m0, s19
	v_lshl_add_u64 v[198:199], s[44:45], 0, v[134:135]
	ds_read_b128 v[190:193], v145 offset:32768
	ds_read_b128 v[202:205], v145 offset:33792
	ds_read_b128 v[206:209], v145 offset:34816
	ds_read_b128 v[214:217], v145 offset:35840
	ds_read_b128 v[218:221], v145 offset:36864
	ds_read_b128 v[222:225], v145 offset:37888
	ds_read_b128 v[226:229], v145 offset:38912
	ds_read_b128 v[230:233], v145 offset:39936
	global_load_lds_dwordx4 v[198:199], off
	v_lshl_add_u64 v[198:199], s[44:45], 0, v[132:133]
	s_mov_b32 m0, s20
	s_nop 0
	global_load_lds_dwordx4 v[198:199], off
	s_setprio 1
	s_waitcnt vmcnt(8)
	s_waitcnt lgkmcnt(0)
	s_barrier
	v_mfma_f32_16x16x32_bf16 v[110:113], v[154:157], v[190:193], v[110:113]
	v_mfma_f32_16x16x32_bf16 v[106:109], v[162:165], v[190:193], v[106:109]
	v_mfma_f32_16x16x32_bf16 v[118:121], v[154:157], v[206:209], v[118:121]
	v_mfma_f32_16x16x32_bf16 v[114:117], v[162:165], v[206:209], v[114:117]
	v_mfma_f32_16x16x32_bf16 v[126:129], v[154:157], v[218:221], v[126:129]
	v_mfma_f32_16x16x32_bf16 v[122:125], v[162:165], v[218:221], v[122:125]
	v_mfma_f32_16x16x32_bf16 v[92:95], v[154:157], v[226:229], v[92:95]
	v_mfma_f32_16x16x32_bf16 v[88:91], v[162:165], v[226:229], v[88:91]
	v_mfma_f32_16x16x32_bf16 v[110:113], v[158:161], v[202:205], v[110:113]
	v_mfma_f32_16x16x32_bf16 v[106:109], v[166:169], v[202:205], v[106:109]
	v_mfma_f32_16x16x32_bf16 v[118:121], v[158:161], v[214:217], v[118:121]
	v_mfma_f32_16x16x32_bf16 v[114:117], v[166:169], v[214:217], v[114:117]
	v_mfma_f32_16x16x32_bf16 v[126:129], v[158:161], v[222:225], v[126:129]
	v_mfma_f32_16x16x32_bf16 v[122:125], v[166:169], v[222:225], v[122:125]
	v_mfma_f32_16x16x32_bf16 v[92:95], v[158:161], v[230:233], v[92:95]
	v_mfma_f32_16x16x32_bf16 v[88:91], v[166:169], v[230:233], v[88:91]
	s_setprio 0
	s_setprio 1
	v_mfma_f32_16x16x32_bf16 v[4:7], v[174:177], v[190:193], v[4:7]
	v_mfma_f32_16x16x32_bf16 v[0:3], v[182:185], v[190:193], v[0:3]
	v_mfma_f32_16x16x32_bf16 v[12:15], v[174:177], v[206:209], v[12:15]
	v_mfma_f32_16x16x32_bf16 v[8:11], v[182:185], v[206:209], v[8:11]
	v_mfma_f32_16x16x32_bf16 v[24:27], v[174:177], v[218:221], v[24:27]
	v_mfma_f32_16x16x32_bf16 v[20:23], v[182:185], v[218:221], v[20:23]
	v_mfma_f32_16x16x32_bf16 v[40:43], v[174:177], v[226:229], v[40:43]
	v_mfma_f32_16x16x32_bf16 v[36:39], v[182:185], v[226:229], v[36:39]
	v_mfma_f32_16x16x32_bf16 v[4:7], v[178:181], v[202:205], v[4:7]
	v_mfma_f32_16x16x32_bf16 v[0:3], v[186:189], v[202:205], v[0:3]
	v_mfma_f32_16x16x32_bf16 v[12:15], v[178:181], v[214:217], v[12:15]
	v_mfma_f32_16x16x32_bf16 v[8:11], v[186:189], v[214:217], v[8:11]
	v_mfma_f32_16x16x32_bf16 v[24:27], v[178:181], v[222:225], v[24:27]
	v_mfma_f32_16x16x32_bf16 v[20:23], v[186:189], v[222:225], v[20:23]
	v_mfma_f32_16x16x32_bf16 v[40:43], v[178:181], v[230:233], v[40:43]
	v_mfma_f32_16x16x32_bf16 v[36:39], v[186:189], v[230:233], v[36:39]
	s_setprio 0
	s_barrier
	s_add_i32 s3, s3, s5
	v_lshl_add_u64 v[146:147], v[146:147], 0, s[30:31]
	s_mov_b32 m0, s3
	ds_read_b128 v[190:193], v145 offset:49152
	ds_read_b128 v[202:205], v145 offset:50176
	ds_read_b128 v[206:209], v145 offset:51200
	ds_read_b128 v[214:217], v145 offset:52224
	ds_read_b128 v[218:221], v145 offset:53248
	ds_read_b128 v[222:225], v145 offset:54272
	ds_read_b128 v[226:229], v145 offset:55296
	ds_read_b128 v[230:233], v145 offset:56320
	global_load_lds_dwordx4 v[146:147], off
	s_add_i32 m0, s3, 0x2000
	s_add_u32 s42, s42, 0x160080
	v_lshl_add_u64 v[146:147], v[150:151], 0, s[30:31]
	s_addc_u32 s43, s43, 0
	s_add_i32 s3, s6, s5
	global_load_lds_dwordx4 v[146:147], off
	v_lshl_add_u64 v[146:147], s[42:43], 0, v[96:97]
	s_mov_b32 m0, s3
	s_nop 0
	global_load_lds_dwordx4 v[146:147], off
	v_lshl_add_u64 v[146:147], s[42:43], 0, v[130:131]
	s_add_i32 m0, s3, 0x2000
	s_nop 0
	global_load_lds_dwordx4 v[146:147], off
	v_lshl_add_u64 v[146:147], v[170:171], 0, s[30:31]
	s_mov_b32 m0, s37
	s_nop 0
	global_load_lds_dwordx4 v[146:147], off
	v_lshl_add_u64 v[146:147], v[194:195], 0, s[30:31]
	s_mov_b32 m0, s52
	s_nop 0
	global_load_lds_dwordx4 v[146:147], off
	s_setprio 1
	s_waitcnt vmcnt(8)
	s_waitcnt lgkmcnt(0)
	s_barrier
	v_mfma_f32_16x16x32_bf16 v[102:105], v[154:157], v[190:193], v[102:105]
	v_mfma_f32_16x16x32_bf16 v[98:101], v[162:165], v[190:193], v[98:101]
	v_mfma_f32_16x16x32_bf16 v[84:87], v[154:157], v[206:209], v[84:87]
	v_mfma_f32_16x16x32_bf16 v[80:83], v[162:165], v[206:209], v[80:83]
	v_mfma_f32_16x16x32_bf16 v[68:71], v[154:157], v[218:221], v[68:71]
	v_mfma_f32_16x16x32_bf16 v[64:67], v[162:165], v[218:221], v[64:67]
	v_mfma_f32_16x16x32_bf16 v[44:47], v[154:157], v[226:229], v[44:47]
	v_mfma_f32_16x16x32_bf16 v[32:35], v[162:165], v[226:229], v[32:35]
	v_mfma_f32_16x16x32_bf16 v[102:105], v[158:161], v[202:205], v[102:105]
	v_mfma_f32_16x16x32_bf16 v[98:101], v[166:169], v[202:205], v[98:101]
	v_mfma_f32_16x16x32_bf16 v[84:87], v[158:161], v[214:217], v[84:87]
	v_mfma_f32_16x16x32_bf16 v[80:83], v[166:169], v[214:217], v[80:83]
	v_mfma_f32_16x16x32_bf16 v[68:71], v[158:161], v[222:225], v[68:71]
	v_mfma_f32_16x16x32_bf16 v[64:67], v[166:169], v[222:225], v[64:67]
	v_mfma_f32_16x16x32_bf16 v[44:47], v[158:161], v[230:233], v[44:47]
	v_mfma_f32_16x16x32_bf16 v[32:35], v[166:169], v[230:233], v[32:35]
	s_setprio 0
	s_setprio 1
	v_mfma_f32_16x16x32_bf16 v[60:63], v[174:177], v[190:193], v[60:63]
	v_mfma_f32_16x16x32_bf16 v[56:59], v[182:185], v[190:193], v[56:59]
	v_mfma_f32_16x16x32_bf16 v[76:79], v[174:177], v[206:209], v[76:79]
	v_mfma_f32_16x16x32_bf16 v[72:75], v[182:185], v[206:209], v[72:75]
	v_mfma_f32_16x16x32_bf16 v[52:55], v[174:177], v[218:221], v[52:55]
	v_mfma_f32_16x16x32_bf16 v[48:51], v[182:185], v[218:221], v[48:51]
	v_mfma_f32_16x16x32_bf16 v[28:31], v[174:177], v[226:229], v[28:31]
	v_mfma_f32_16x16x32_bf16 v[16:19], v[182:185], v[226:229], v[16:19]
	v_mfma_f32_16x16x32_bf16 v[60:63], v[178:181], v[202:205], v[60:63]
	v_mfma_f32_16x16x32_bf16 v[56:59], v[186:189], v[202:205], v[56:59]
	v_mfma_f32_16x16x32_bf16 v[76:79], v[178:181], v[214:217], v[76:79]
	v_mfma_f32_16x16x32_bf16 v[72:75], v[186:189], v[214:217], v[72:75]
	v_mfma_f32_16x16x32_bf16 v[52:55], v[178:181], v[222:225], v[52:55]
	v_mfma_f32_16x16x32_bf16 v[48:51], v[186:189], v[222:225], v[48:51]
	v_mfma_f32_16x16x32_bf16 v[28:31], v[178:181], v[230:233], v[28:31]
	v_mfma_f32_16x16x32_bf16 v[16:19], v[186:189], v[230:233], v[16:19]
	s_setprio 0
	s_barrier
	s_add_i32 s2, s2, 2
	s_add_u32 s34, s34, 0x100
	s_addc_u32 s35, s35, 0
	s_cmpk_gt_u32 s2, 0x55
	s_cbranch_scc0 .LBB0_1357
	s_nop 0
	s_nop 0
	s_nop 0
	s_nop 0
	s_and_b64 vcc, exec, s[12:13]
	s_cbranch_vccz .LBB0_1360
	s_barrier

.LBB0_1413:
	s_add_u32 s24, s22, 0x100
	s_addc_u32 s25, s23, 0
	s_add_i32 s45, 0, 0x10000
	s_cmpk_eq_i32 s6, 0x54
	s_cselect_b32 s39, s13, s25
	s_cselect_b32 s38, s12, s24
	s_cselect_b32 s35, s15, s3
	s_cselect_b32 s34, s14, s2
	s_add_i32 s46, 0, 0x14000
	v_add_u32_e32 v142, s45, v155
	v_add_u32_e32 v152, s46, v155
	ds_read_b128 v[130:133], v142
	ds_read_b128 v[134:137], v142 offset:1024
	ds_read_b128 v[138:141], v142 offset:2048
	ds_read_b128 v[142:145], v142 offset:3072
	ds_read_b128 v[158:161], v152
	ds_read_b128 v[162:165], v152 offset:1024
	ds_read_b128 v[166:169], v152 offset:2048
	ds_read_b128 v[170:173], v152 offset:3072
	v_lshl_add_u64 v[152:153], s[22:23], 0, v[148:149]
	s_add_i32 m0, s5, 0xc000
	ds_read_b128 v[174:177], v157
	ds_read_b128 v[178:181], v157 offset:1024
	ds_read_b128 v[182:185], v157 offset:2048
	ds_read_b128 v[186:189], v157 offset:3072
	ds_read_b128 v[190:193], v157 offset:4096
	ds_read_b128 v[202:205], v157 offset:5120
	ds_read_b128 v[206:209], v157 offset:6144
	ds_read_b128 v[214:217], v157 offset:7168
	global_load_lds_dwordx4 v[152:153], off
	v_lshl_add_u64 v[152:153], s[22:23], 0, v[150:151]
	s_add_i32 m0, s5, 0xe000
	s_nop 0
	global_load_lds_dwordx4 v[152:153], off
	s_setprio 1
	s_waitcnt vmcnt(8)
	s_waitcnt lgkmcnt(0)
	s_barrier
	v_mfma_f32_16x16x32_bf16 v[126:129], v[130:133], v[174:177], v[126:129]
	v_mfma_f32_16x16x32_bf16 v[122:125], v[138:141], v[174:177], v[122:125]
	v_mfma_f32_16x16x32_bf16 v[114:117], v[130:133], v[182:185], v[114:117]
	v_mfma_f32_16x16x32_bf16 v[110:113], v[138:141], v[182:185], v[110:113]
	v_mfma_f32_16x16x32_bf16 v[98:101], v[130:133], v[190:193], v[98:101]
	v_mfma_f32_16x16x32_bf16 v[92:95], v[138:141], v[190:193], v[92:95]
	v_mfma_f32_16x16x32_bf16 v[80:83], v[130:133], v[206:209], v[80:83]
	v_mfma_f32_16x16x32_bf16 v[76:79], v[138:141], v[206:209], v[76:79]
	v_mfma_f32_16x16x32_bf16 v[126:129], v[134:137], v[178:181], v[126:129]
	v_mfma_f32_16x16x32_bf16 v[122:125], v[142:145], v[178:181], v[122:125]
	v_mfma_f32_16x16x32_bf16 v[114:117], v[134:137], v[186:189], v[114:117]
	v_mfma_f32_16x16x32_bf16 v[110:113], v[142:145], v[186:189], v[110:113]
	v_mfma_f32_16x16x32_bf16 v[98:101], v[134:137], v[202:205], v[98:101]
	v_mfma_f32_16x16x32_bf16 v[92:95], v[142:145], v[202:205], v[92:95]
	v_mfma_f32_16x16x32_bf16 v[80:83], v[134:137], v[214:217], v[80:83]
	v_mfma_f32_16x16x32_bf16 v[76:79], v[142:145], v[214:217], v[76:79]
	s_setprio 0
	s_setprio 1
	v_mfma_f32_16x16x32_bf16 v[118:121], v[158:161], v[174:177], v[118:121]
	v_mfma_f32_16x16x32_bf16 v[106:109], v[166:169], v[174:177], v[106:109]
	v_mfma_f32_16x16x32_bf16 v[102:105], v[158:161], v[182:185], v[102:105]
	v_mfma_f32_16x16x32_bf16 v[88:91], v[166:169], v[182:185], v[88:91]
	v_mfma_f32_16x16x32_bf16 v[84:87], v[158:161], v[190:193], v[84:87]
	v_mfma_f32_16x16x32_bf16 v[72:75], v[166:169], v[190:193], v[72:75]
	v_mfma_f32_16x16x32_bf16 v[68:71], v[158:161], v[206:209], v[68:71]
	v_mfma_f32_16x16x32_bf16 v[64:67], v[166:169], v[206:209], v[64:67]
	v_mfma_f32_16x16x32_bf16 v[118:121], v[162:165], v[178:181], v[118:121]
	v_mfma_f32_16x16x32_bf16 v[106:109], v[170:173], v[178:181], v[106:109]
	v_mfma_f32_16x16x32_bf16 v[102:105], v[162:165], v[186:189], v[102:105]
	v_mfma_f32_16x16x32_bf16 v[88:91], v[170:173], v[186:189], v[88:91]
	v_mfma_f32_16x16x32_bf16 v[84:87], v[162:165], v[202:205], v[84:87]
	v_mfma_f32_16x16x32_bf16 v[72:75], v[170:173], v[202:205], v[72:75]
	v_mfma_f32_16x16x32_bf16 v[68:71], v[162:165], v[214:217], v[68:71]
	v_mfma_f32_16x16x32_bf16 v[64:67], v[170:173], v[214:217], v[64:67]
	s_setprio 0
	s_barrier
	s_add_i32 s22, s45, s4
	v_lshl_add_u64 v[152:153], s[34:35], 0, v[96:97]
	s_mov_b32 m0, s22
	ds_read_b128 v[174:177], v157 offset:16384
	ds_read_b128 v[178:181], v157 offset:17408
	ds_read_b128 v[182:185], v157 offset:18432
	ds_read_b128 v[186:189], v157 offset:19456
	ds_read_b128 v[190:193], v157 offset:20480
	ds_read_b128 v[202:205], v157 offset:21504
	ds_read_b128 v[206:209], v157 offset:22528
	ds_read_b128 v[214:217], v157 offset:23552
	global_load_lds_dwordx4 v[152:153], off
	s_add_i32 m0, s22, 0x2000
	s_add_u32 s22, s34, 0x160000
	v_lshl_add_u64 v[194:195], s[34:35], 0, v[146:147]
	s_addc_u32 s23, s35, 0
	s_add_i32 s45, s46, s4
	global_load_lds_dwordx4 v[194:195], off
	v_lshl_add_u64 v[198:199], s[22:23], 0, v[96:97]
	s_mov_b32 m0, s45
	v_lshl_add_u64 v[200:201], s[38:39], 0, v[146:147]
	global_load_lds_dwordx4 v[198:199], off
	v_lshl_add_u64 v[198:199], s[22:23], 0, v[146:147]
	s_add_i32 m0, s45, 0x2000
	s_nop 0
	global_load_lds_dwordx4 v[198:199], off
	v_lshl_add_u64 v[198:199], s[38:39], 0, v[96:97]
	s_mov_b32 m0, s5
	s_nop 0
	global_load_lds_dwordx4 v[198:199], off
	s_mov_b32 m0, s17
	s_nop 0
	global_load_lds_dwordx4 v[200:201], off
	s_setprio 1
	s_waitcnt vmcnt(8)
	s_waitcnt lgkmcnt(0)
	s_barrier
	v_mfma_f32_16x16x32_bf16 v[60:63], v[130:133], v[174:177], v[60:63]
	v_mfma_f32_16x16x32_bf16 v[56:59], v[138:141], v[174:177], v[56:59]
	v_mfma_f32_16x16x32_bf16 v[48:51], v[130:133], v[182:185], v[48:51]
	v_mfma_f32_16x16x32_bf16 v[44:47], v[138:141], v[182:185], v[44:47]
	v_mfma_f32_16x16x32_bf16 v[32:35], v[130:133], v[190:193], v[32:35]
	v_mfma_f32_16x16x32_bf16 v[28:31], v[138:141], v[190:193], v[28:31]
	v_mfma_f32_16x16x32_bf16 v[16:19], v[130:133], v[206:209], v[16:19]
	v_mfma_f32_16x16x32_bf16 v[12:15], v[138:141], v[206:209], v[12:15]
	v_mfma_f32_16x16x32_bf16 v[60:63], v[134:137], v[178:181], v[60:63]
	v_mfma_f32_16x16x32_bf16 v[56:59], v[142:145], v[178:181], v[56:59]
	v_mfma_f32_16x16x32_bf16 v[48:51], v[134:137], v[186:189], v[48:51]
	v_mfma_f32_16x16x32_bf16 v[44:47], v[142:145], v[186:189], v[44:47]
	v_mfma_f32_16x16x32_bf16 v[32:35], v[134:137], v[202:205], v[32:35]
	v_mfma_f32_16x16x32_bf16 v[28:31], v[142:145], v[202:205], v[28:31]
	v_mfma_f32_16x16x32_bf16 v[16:19], v[134:137], v[214:217], v[16:19]
	v_mfma_f32_16x16x32_bf16 v[12:15], v[142:145], v[214:217], v[12:15]
	s_setprio 0
	s_setprio 1
	v_mfma_f32_16x16x32_bf16 v[52:55], v[158:161], v[174:177], v[52:55]
	v_mfma_f32_16x16x32_bf16 v[40:43], v[166:169], v[174:177], v[40:43]
	v_mfma_f32_16x16x32_bf16 v[36:39], v[158:161], v[182:185], v[36:39]
	v_mfma_f32_16x16x32_bf16 v[24:27], v[166:169], v[182:185], v[24:27]
	v_mfma_f32_16x16x32_bf16 v[20:23], v[158:161], v[190:193], v[20:23]
	v_mfma_f32_16x16x32_bf16 v[8:11], v[166:169], v[190:193], v[8:11]
	v_mfma_f32_16x16x32_bf16 v[4:7], v[158:161], v[206:209], v[4:7]
	v_mfma_f32_16x16x32_bf16 v[0:3], v[166:169], v[206:209], v[0:3]
	v_mfma_f32_16x16x32_bf16 v[52:55], v[162:165], v[178:181], v[52:55]
	v_mfma_f32_16x16x32_bf16 v[40:43], v[170:173], v[178:181], v[40:43]
	v_mfma_f32_16x16x32_bf16 v[36:39], v[162:165], v[186:189], v[36:39]
	v_mfma_f32_16x16x32_bf16 v[24:27], v[170:173], v[186:189], v[24:27]
	v_mfma_f32_16x16x32_bf16 v[20:23], v[162:165], v[202:205], v[20:23]
	v_mfma_f32_16x16x32_bf16 v[8:11], v[170:173], v[202:205], v[8:11]
	v_mfma_f32_16x16x32_bf16 v[4:7], v[162:165], v[214:217], v[4:7]
	v_mfma_f32_16x16x32_bf16 v[0:3], v[170:173], v[214:217], v[0:3]
	s_setprio 0
	s_barrier
	s_add_i32 s45, 0, 0x18000
	s_add_i32 s46, 0, 0x1c000
	v_add_u32_e32 v142, s45, v155
	v_add_u32_e32 v170, s46, v155
	ds_read_b128 v[130:133], v142
	ds_read_b128 v[134:137], v142 offset:1024
	ds_read_b128 v[138:141], v142 offset:2048
	ds_read_b128 v[142:145], v142 offset:3072
	ds_read_b128 v[158:161], v170
	ds_read_b128 v[162:165], v170 offset:1024
	ds_read_b128 v[166:169], v170 offset:2048
	ds_read_b128 v[170:173], v170 offset:3072
	s_add_u32 s22, s38, 0x160000
	s_addc_u32 s23, s39, 0
	s_mov_b32 m0, s18
	v_lshl_add_u64 v[218:219], s[22:23], 0, v[96:97]
	ds_read_b128 v[174:177], v157 offset:32768
	ds_read_b128 v[178:181], v157 offset:33792
	ds_read_b128 v[182:185], v157 offset:34816
	ds_read_b128 v[186:189], v157 offset:35840
	ds_read_b128 v[190:193], v157 offset:36864
	ds_read_b128 v[202:205], v157 offset:37888
	ds_read_b128 v[206:209], v157 offset:38912
	ds_read_b128 v[214:217], v157 offset:39936
	global_load_lds_dwordx4 v[218:219], off
	v_lshl_add_u64 v[218:219], s[22:23], 0, v[146:147]
	s_mov_b32 m0, s19
	s_nop 0
	global_load_lds_dwordx4 v[218:219], off
	s_setprio 1
	s_waitcnt vmcnt(8)
	s_waitcnt lgkmcnt(0)
	s_barrier
	v_mfma_f32_16x16x32_bf16 v[126:129], v[130:133], v[174:177], v[126:129]
	v_mfma_f32_16x16x32_bf16 v[122:125], v[138:141], v[174:177], v[122:125]
	v_mfma_f32_16x16x32_bf16 v[114:117], v[130:133], v[182:185], v[114:117]
	v_mfma_f32_16x16x32_bf16 v[110:113], v[138:141], v[182:185], v[110:113]
	v_mfma_f32_16x16x32_bf16 v[98:101], v[130:133], v[190:193], v[98:101]
	v_mfma_f32_16x16x32_bf16 v[92:95], v[138:141], v[190:193], v[92:95]
	v_mfma_f32_16x16x32_bf16 v[80:83], v[130:133], v[206:209], v[80:83]
	v_mfma_f32_16x16x32_bf16 v[76:79], v[138:141], v[206:209], v[76:79]
	v_mfma_f32_16x16x32_bf16 v[126:129], v[134:137], v[178:181], v[126:129]
	v_mfma_f32_16x16x32_bf16 v[122:125], v[142:145], v[178:181], v[122:125]
	v_mfma_f32_16x16x32_bf16 v[114:117], v[134:137], v[186:189], v[114:117]
	v_mfma_f32_16x16x32_bf16 v[110:113], v[142:145], v[186:189], v[110:113]
	v_mfma_f32_16x16x32_bf16 v[98:101], v[134:137], v[202:205], v[98:101]
	v_mfma_f32_16x16x32_bf16 v[92:95], v[142:145], v[202:205], v[92:95]
	v_mfma_f32_16x16x32_bf16 v[80:83], v[134:137], v[214:217], v[80:83]
	v_mfma_f32_16x16x32_bf16 v[76:79], v[142:145], v[214:217], v[76:79]
	s_setprio 0
	s_setprio 1
	v_mfma_f32_16x16x32_bf16 v[118:121], v[158:161], v[174:177], v[118:121]
	v_mfma_f32_16x16x32_bf16 v[106:109], v[166:169], v[174:177], v[106:109]
	v_mfma_f32_16x16x32_bf16 v[102:105], v[158:161], v[182:185], v[102:105]
	v_mfma_f32_16x16x32_bf16 v[88:91], v[166:169], v[182:185], v[88:91]
	v_mfma_f32_16x16x32_bf16 v[84:87], v[158:161], v[190:193], v[84:87]
	v_mfma_f32_16x16x32_bf16 v[72:75], v[166:169], v[190:193], v[72:75]
	v_mfma_f32_16x16x32_bf16 v[68:71], v[158:161], v[206:209], v[68:71]
	v_mfma_f32_16x16x32_bf16 v[64:67], v[166:169], v[206:209], v[64:67]
	v_mfma_f32_16x16x32_bf16 v[118:121], v[162:165], v[178:181], v[118:121]
	v_mfma_f32_16x16x32_bf16 v[106:109], v[170:173], v[178:181], v[106:109]
	v_mfma_f32_16x16x32_bf16 v[102:105], v[162:165], v[186:189], v[102:105]
	v_mfma_f32_16x16x32_bf16 v[88:91], v[170:173], v[186:189], v[88:91]
	v_mfma_f32_16x16x32_bf16 v[84:87], v[162:165], v[202:205], v[84:87]
	v_mfma_f32_16x16x32_bf16 v[72:75], v[170:173], v[202:205], v[72:75]
	v_mfma_f32_16x16x32_bf16 v[68:71], v[162:165], v[214:217], v[68:71]
	v_mfma_f32_16x16x32_bf16 v[64:67], v[170:173], v[214:217], v[64:67]
	s_setprio 0
	s_barrier
	s_add_i32 s22, s45, s4
	v_lshl_add_u64 v[152:153], v[152:153], 0, s[30:31]
	s_mov_b32 m0, s22
	ds_read_b128 v[174:177], v157 offset:49152
	ds_read_b128 v[178:181], v157 offset:50176
	ds_read_b128 v[182:185], v157 offset:51200
	ds_read_b128 v[186:189], v157 offset:52224
	ds_read_b128 v[190:193], v157 offset:53248
	ds_read_b128 v[202:205], v157 offset:54272
	ds_read_b128 v[206:209], v157 offset:55296
	ds_read_b128 v[214:217], v157 offset:56320
	global_load_lds_dwordx4 v[152:153], off
	s_add_i32 m0, s22, 0x2000
	s_add_u32 s22, s34, 0x160080
	v_lshl_add_u64 v[152:153], v[194:195], 0, s[30:31]
	s_addc_u32 s23, s35, 0
	s_add_i32 s34, s46, s4
	global_load_lds_dwordx4 v[152:153], off
	v_lshl_add_u64 v[152:153], s[22:23], 0, v[96:97]
	s_mov_b32 m0, s34
	s_nop 0
	global_load_lds_dwordx4 v[152:153], off
	v_lshl_add_u64 v[152:153], s[22:23], 0, v[146:147]
	s_add_i32 m0, s34, 0x2000
	s_nop 0
	global_load_lds_dwordx4 v[152:153], off
	v_lshl_add_u64 v[152:153], v[198:199], 0, s[30:31]
	s_mov_b32 m0, s20
	s_nop 0
	global_load_lds_dwordx4 v[152:153], off
	v_lshl_add_u64 v[152:153], v[200:201], 0, s[30:31]
	s_mov_b32 m0, s36
	s_nop 0
	global_load_lds_dwordx4 v[152:153], off
	s_setprio 1
	s_waitcnt vmcnt(8)
	s_waitcnt lgkmcnt(0)
	s_barrier
	v_mfma_f32_16x16x32_bf16 v[60:63], v[130:133], v[174:177], v[60:63]
	v_mfma_f32_16x16x32_bf16 v[56:59], v[138:141], v[174:177], v[56:59]
	v_mfma_f32_16x16x32_bf16 v[48:51], v[130:133], v[182:185], v[48:51]
	v_mfma_f32_16x16x32_bf16 v[44:47], v[138:141], v[182:185], v[44:47]
	v_mfma_f32_16x16x32_bf16 v[32:35], v[130:133], v[190:193], v[32:35]
	v_mfma_f32_16x16x32_bf16 v[28:31], v[138:141], v[190:193], v[28:31]
	v_mfma_f32_16x16x32_bf16 v[16:19], v[130:133], v[206:209], v[16:19]
	v_mfma_f32_16x16x32_bf16 v[12:15], v[138:141], v[206:209], v[12:15]
	v_mfma_f32_16x16x32_bf16 v[60:63], v[134:137], v[178:181], v[60:63]
	v_mfma_f32_16x16x32_bf16 v[56:59], v[142:145], v[178:181], v[56:59]
	v_mfma_f32_16x16x32_bf16 v[48:51], v[134:137], v[186:189], v[48:51]
	v_mfma_f32_16x16x32_bf16 v[44:47], v[142:145], v[186:189], v[44:47]
	v_mfma_f32_16x16x32_bf16 v[32:35], v[134:137], v[202:205], v[32:35]
	v_mfma_f32_16x16x32_bf16 v[28:31], v[142:145], v[202:205], v[28:31]
	v_mfma_f32_16x16x32_bf16 v[16:19], v[134:137], v[214:217], v[16:19]
	v_mfma_f32_16x16x32_bf16 v[12:15], v[142:145], v[214:217], v[12:15]
	s_setprio 0
	s_setprio 1
	v_mfma_f32_16x16x32_bf16 v[52:55], v[158:161], v[174:177], v[52:55]
	v_mfma_f32_16x16x32_bf16 v[40:43], v[166:169], v[174:177], v[40:43]
	v_mfma_f32_16x16x32_bf16 v[36:39], v[158:161], v[182:185], v[36:39]
	v_mfma_f32_16x16x32_bf16 v[24:27], v[166:169], v[182:185], v[24:27]
	v_mfma_f32_16x16x32_bf16 v[20:23], v[158:161], v[190:193], v[20:23]
	v_mfma_f32_16x16x32_bf16 v[8:11], v[166:169], v[190:193], v[8:11]
	v_mfma_f32_16x16x32_bf16 v[4:7], v[158:161], v[206:209], v[4:7]
	v_mfma_f32_16x16x32_bf16 v[0:3], v[166:169], v[206:209], v[0:3]
	v_mfma_f32_16x16x32_bf16 v[52:55], v[162:165], v[178:181], v[52:55]
	v_mfma_f32_16x16x32_bf16 v[40:43], v[170:173], v[178:181], v[40:43]
	v_mfma_f32_16x16x32_bf16 v[36:39], v[162:165], v[186:189], v[36:39]
	v_mfma_f32_16x16x32_bf16 v[24:27], v[170:173], v[186:189], v[24:27]
	v_mfma_f32_16x16x32_bf16 v[20:23], v[162:165], v[202:205], v[20:23]
	v_mfma_f32_16x16x32_bf16 v[8:11], v[170:173], v[202:205], v[8:11]
	v_mfma_f32_16x16x32_bf16 v[4:7], v[162:165], v[214:217], v[4:7]
	v_mfma_f32_16x16x32_bf16 v[0:3], v[170:173], v[214:217], v[0:3]
	s_setprio 0
	s_barrier
	s_add_i32 s6, s6, 2
	s_add_u32 s2, s2, 0x100
	s_addc_u32 s3, s3, 0
	s_cmpk_gt_u32 s6, 0x55
	s_mov_b64 s[22:23], s[24:25]
	s_cbranch_scc0 .LBB0_1413
	s_nop 0
	s_nop 0
	s_nop 0
	s_nop 0
	s_and_b64 vcc, exec, s[10:11]
	s_cbranch_vccz .LBB0_1416
	s_barrier
